# speedup vs baseline: 1.0406x; 1.0406x over previous
; template <int MODE>
; __device__ __forceinline__ void phase_rows(const PRef& p, const float* __restrict__ vsrc, const float* __restrict__ g1, const float* __restrict__ g2, float coef, int nsplit) {
;     ...
; #pragma unroll
;       for (int i = 0; i < 4; ++i) ss += v[i].x * v[i].x + v[i].y * v[i].y + v[i].z * v[i].z + v[i].w * v[i].w;
;       ss = wave_sum(ss);
;       const float r = rsqrtf(ss * (1.f / DM) + RMS_EPS) * coef;
; #pragma unroll
;       for (int i = 0; i < 4; ++i) {
;         const f32x4v bt = __builtin_nontemporal_load(reinterpret_cast<const f32x4v*>(bs) + lane + 64 * i); const float4 b = make_float4(bt[0], bt[1], bt[2], bt[3]);
;         float4 g = reinterpret_cast<const float4*>(g1)[lane + 64 * i];
;         h[i].x = b.x + v[i].x * r * g.x; h[i].y = b.y + v[i].y * r * g.y; h[i].z = b.z + v[i].z * r * g.z; h[i].w = b.w + v[i].w * r * g.w;
;       }
;       if (MODE != 3) {
;         float4* hd = reinterpret_cast<float4*>(hbuf + (size_t)row * DM);
; #pragma unroll
;         for (int i = 0; i < 4; ++i) __builtin_nontemporal_store(f32x4v{h[i].x, h[i].y, h[i].z, h[i].w}, reinterpret_cast<f32x4v*>(hd) + lane + 64 * i);
;       }
;     }
;     float ss2 = 0.f;
; #pragma unroll
;     for (int i = 0; i < 4; ++i) ss2 += h[i].x * h[i].x + h[i].y * h[i].y + h[i].z * h[i].z + h[i].w * h[i].w;
;     ss2 = wave_sum(ss2);
;     const float r2 = rsqrtf(ss2 * (1.f / DM) + RMS_EPS);
; #pragma unroll
;     for (int i = 0; i < 4; ++i) {
;       float4 g = reinterpret_cast<const float4*>(g2)[lane + 64 * i];
;       float o0 = h[i].x * r2 * g.x, o1 = h[i].y * r2 * g.y, o2 = h[i].z * r2 * g.z, o3 = h[i].w * r2 * g.w;
;       if (MODE == 3) {
;         __builtin_nontemporal_store(f32x4v{o0, o1, o2, o3}, reinterpret_cast<f32x4v*>(hbuf + (size_t)row * DM) + lane + 64 * i);
;       } else {
;         u32x2 w = {cvtpk(o0, o1), cvtpk(o2, o3)};
;         reinterpret_cast<u32x2*>(xn + (size_t)row * DM)[lane + 64 * i] = w;
;       }
;     }
.LBB0_31:
	s_or_b64 exec, exec, s[0:1]
	v_mov_b32_e32 v36, v90
	v_mov_b32_e32 v37, v86
	v_pk_mul_f32 v[36:37], v[36:37], v[36:37]
	v_mov_b32_e32 v38, v91
	v_mov_b32_e32 v39, v87
	v_pk_fma_f32 v[36:37], v[38:39], v[38:39], v[36:37]
	v_mov_b32_e32 v38, v88
	v_mov_b32_e32 v39, v84
	v_pk_fma_f32 v[36:37], v[38:39], v[38:39], v[36:37]
	v_mov_b32_e32 v38, v89
	v_mov_b32_e32 v39, v85
	v_pk_fma_f32 v[36:37], v[38:39], v[38:39], v[36:37]
	v_mov_b32_e32 v38, v44
	v_mov_b32_e32 v39, v94
	v_pk_mul_f32 v[38:39], v[38:39], v[38:39]
	v_mov_b32_e32 v40, v45
	v_mov_b32_e32 v41, v95
	v_pk_fma_f32 v[38:39], v[40:41], v[40:41], v[38:39]
	v_mov_b32_e32 v40, v42
	v_mov_b32_e32 v41, v92
	v_pk_fma_f32 v[38:39], v[40:41], v[40:41], v[38:39]
	v_mov_b32_e32 v40, v43
	v_mov_b32_e32 v41, v93
	v_pk_fma_f32 v[38:39], v[40:41], v[40:41], v[38:39]
	v_add_f32_e32 v0, v36, v37
	v_add_f32_e32 v0, v39, v0
	v_add_f32_e32 v0, v38, v0
	ds_bpermute_b32 v36, v96, v0
	s_mov_b32 s0, 0x800000
	v_lshl_add_u64 v[46:47], v[34:35], 2, v[78:79]
	s_waitcnt lgkmcnt(0)
	v_add_f32_e32 v0, v0, v36
	ds_bpermute_b32 v36, v97, v0
	s_waitcnt lgkmcnt(0)
	v_add_f32_e32 v0, v0, v36
	ds_bpermute_b32 v36, v98, v0
	s_waitcnt lgkmcnt(0)
	v_add_f32_e32 v0, v0, v36
	ds_bpermute_b32 v36, v99, v0
	s_waitcnt lgkmcnt(0)
	v_add_f32_e32 v0, v0, v36
	ds_bpermute_b32 v36, v100, v0
	s_waitcnt lgkmcnt(0)
	v_add_f32_e32 v0, v0, v36
	ds_bpermute_b32 v36, v101, v0
	s_waitcnt lgkmcnt(0)
	v_add_f32_e32 v0, v0, v36
	v_fmamk_f32 v0, v0, 0x3a800000, v190
	v_cmp_gt_f32_e32 vcc, s0, v0
	v_mul_f32_e32 v36, 0x4b800000, v0
	s_nop 0
	v_cndmask_b32_e32 v0, v0, v36, vcc
	v_rsq_f32_e32 v0, v0
	s_nop 0
	v_mul_f32_e32 v36, 0x45800000, v0
	v_cndmask_b32_e32 v0, v0, v36, vcc
	v_mul_f32_e32 v0, 0.5, v0
	v_pk_mul_f32 v[56:57], v[86:87], v[0:1] op_sel_hi:[1,0]
	v_pk_mul_f32 v[44:45], v[44:45], v[0:1] op_sel_hi:[1,0]
	s_waitcnt vmcnt(0) lgkmcnt(0)
	v_pk_fma_f32 v[48:49], v[2:3], v[56:57], v[212:213]
	v_pk_mul_f32 v[56:57], v[84:85], v[0:1] op_sel_hi:[1,0]
	v_mov_b32_e32 v58, v49
	v_pk_fma_f32 v[50:51], v[4:5], v[56:57], v[214:215]
	v_pk_mul_f32 v[56:57], v[90:91], v[0:1] op_sel_hi:[1,0]
	v_pk_fma_f32 v[44:45], v[22:23], v[44:45], v[224:225]
	v_pk_fma_f32 v[52:53], v[6:7], v[56:57], v[216:217]
	v_pk_mul_f32 v[56:57], v[88:89], v[0:1] op_sel_hi:[1,0]
	v_mov_b32_e32 v59, v53
	v_pk_fma_f32 v[54:55], v[8:9], v[56:57], v[218:219]
	v_mov_b32_e32 v56, v48
	v_mov_b32_e32 v57, v52
	v_pk_mul_f32 v[58:59], v[58:59], v[58:59]
	v_pk_mul_f32 v[34:35], v[42:43], v[0:1] op_sel_hi:[1,0]
	v_pk_fma_f32 v[56:57], v[56:57], v[56:57], v[58:59]
	v_mov_b32_e32 v58, v50
	v_mov_b32_e32 v59, v54
	v_pk_fma_f32 v[56:57], v[58:59], v[58:59], v[56:57]
	v_pk_mul_f32 v[58:59], v[94:95], v[0:1] op_sel_hi:[1,0]
	v_pk_fma_f32 v[42:43], v[24:25], v[34:35], v[226:227]
	v_pk_fma_f32 v[38:39], v[18:19], v[58:59], v[220:221]
	v_pk_mul_f32 v[58:59], v[92:93], v[0:1] op_sel_hi:[1,0]
	v_mov_b32_e32 v36, v45
	v_mov_b32_e32 v37, v39
	v_pk_fma_f32 v[40:41], v[20:21], v[58:59], v[222:223]
	v_mov_b32_e32 v34, v44
	v_mov_b32_e32 v35, v38
	v_pk_mul_f32 v[36:37], v[36:37], v[36:37]
	v_mov_b32_e32 v60, v51
	v_mov_b32_e32 v61, v55
	v_pk_fma_f32 v[34:35], v[34:35], v[34:35], v[36:37]
	v_mov_b32_e32 v36, v42
	v_mov_b32_e32 v37, v40
	v_pk_fma_f32 v[56:57], v[60:61], v[60:61], v[56:57]
	v_mov_b32_e32 v58, v43
	v_mov_b32_e32 v59, v41
	v_pk_fma_f32 v[34:35], v[36:37], v[36:37], v[34:35]
	v_add_f32_e32 v0, v56, v57
	v_pk_fma_f32 v[34:35], v[58:59], v[58:59], v[34:35]
	s_nop 0
	v_add_f32_e32 v0, v35, v0
	v_add_f32_e32 v0, v34, v0
	ds_bpermute_b32 v34, v96, v0
	s_waitcnt lgkmcnt(0)
	v_add_f32_e32 v0, v0, v34
	ds_bpermute_b32 v34, v97, v0
	s_waitcnt lgkmcnt(0)
	v_add_f32_e32 v0, v0, v34
	ds_bpermute_b32 v34, v98, v0
	s_waitcnt lgkmcnt(0)
	v_add_f32_e32 v0, v0, v34
	ds_bpermute_b32 v34, v99, v0
	s_waitcnt lgkmcnt(0)
	v_add_f32_e32 v0, v0, v34
	ds_bpermute_b32 v34, v100, v0
	s_waitcnt lgkmcnt(0)
	v_add_f32_e32 v0, v0, v34
	ds_bpermute_b32 v34, v101, v0
	s_waitcnt lgkmcnt(0)
	v_add_f32_e32 v0, v0, v34
	v_fmamk_f32 v0, v0, 0x3a800000, v190
	v_cmp_gt_f32_e32 vcc, s0, v0
	v_mul_f32_e32 v34, 0x4b800000, v0
	v_readlane_b32 s0, v254, 21
	v_cndmask_b32_e32 v0, v0, v34, vcc
	v_rsq_f32_e32 v0, v0
	v_add_u32_e32 v76, s0, v76
	s_movk_i32 s0, 0x40ff
	v_mul_f32_e32 v34, 0x45800000, v0
	v_cndmask_b32_e32 v0, v0, v34, vcc
	v_pk_mul_f32 v[34:35], v[48:49], v[0:1] op_sel_hi:[1,0]
	v_pk_mul_f32 v[36:37], v[50:51], v[0:1] op_sel_hi:[1,0]
	v_pk_mul_f32 v[34:35], v[10:11], v[34:35]
	v_pk_mul_f32 v[36:37], v[12:13], v[36:37]
	flat_store_dwordx4 v[46:47], v[34:37] nt
	v_cmp_lt_i32_e32 vcc, s0, v76
	s_or_b64 s[8:9], vcc, s[8:9]
	v_pk_mul_f32 v[34:35], v[52:53], v[0:1] op_sel_hi:[1,0]
	v_pk_mul_f32 v[36:37], v[54:55], v[0:1] op_sel_hi:[1,0]
	v_pk_mul_f32 v[34:35], v[14:15], v[34:35]
	v_pk_mul_f32 v[36:37], v[16:17], v[36:37]
	flat_store_dwordx4 v[46:47], v[34:37] offset:1024 nt
	s_nop 1
	v_pk_mul_f32 v[34:35], v[38:39], v[0:1] op_sel_hi:[1,0]
	v_pk_mul_f32 v[36:37], v[40:41], v[0:1] op_sel_hi:[1,0]
	v_pk_mul_f32 v[34:35], v[26:27], v[34:35]
	v_pk_mul_f32 v[36:37], v[28:29], v[36:37]
	flat_store_dwordx4 v[46:47], v[34:37] offset:2048 nt
	s_nop 1
	v_pk_mul_f32 v[34:35], v[44:45], v[0:1] op_sel_hi:[1,0]
	v_pk_mul_f32 v[36:37], v[42:43], v[0:1] op_sel_hi:[1,0]
	v_pk_mul_f32 v[34:35], v[30:31], v[34:35]
	v_pk_mul_f32 v[36:37], v[32:33], v[36:37]
	flat_store_dwordx4 v[46:47], v[34:37] offset:3072 nt
	s_andn2_b64 exec, exec, s[8:9]
	s_cbranch_execz .LBB0_39
;   __device__ __forceinline__ unsigned char* ws() const { return reinterpret_cast<unsigned char*>(ld64(27 * 8)); }
; template <int MODE>
; __device__ __forceinline__ void phase_rows(const PRef& p, const float* __restrict__ vsrc, const float* __restrict__ g1, const float* __restrict__ g2, float coef, int nsplit) {
;     ...
;       if (row < MP) {
; #pragma unroll
;         for (int i = 0; i < 4; ++i) { const u32x2 q = vs[lane + 64 * i];
;           v[i] = make_float4(__uint_as_float(q[0] << 16), __uint_as_float(q[0] & 0xffff0000u), __uint_as_float(q[1] << 16), __uint_as_float(q[1] & 0xffff0000u)); }
;       } else {
;         const float4* ps = reinterpret_cast<const float4*>((const float*)(p.ws() + WS_PART) + (size_t)(row - MP) * DM);
; #pragma unroll
;         for (int i = 0; i < 4; ++i) v[i] = ps[lane + 64 * i];
;         for (int k = 1; k < nsplit; ++k) {
; #pragma unroll
;           for (int i = 0; i < 4; ++i) { float4 t = ps[(size_t)k * (MS * DM / 4) + lane + 64 * i]; v[i].x += t.x; v[i].y += t.y; v[i].z += t.z; v[i].w += t.w; }
;     ...
;         const f32x4v bt = __builtin_nontemporal_load(reinterpret_cast<const f32x4v*>(bs) + lane + 64 * i); const float4 b = make_float4(bt[0], bt[1], bt[2], bt[3]);
.LBB0_32:
	v_ashrrev_i32_e32 v241, 31, v76
	v_mov_b32_e32 v240, v76
	v_lshlrev_b64 v[240:241], 10, v[240:241]
	v_lshl_add_u64 v[240:241], v[240:241], 2, v[78:79]
	flat_load_dwordx4 v[212:215], v[240:241] nt
	flat_load_dwordx4 v[216:219], v[240:241] offset:1024 nt
	flat_load_dwordx4 v[220:223], v[240:241] offset:2048 nt
	flat_load_dwordx4 v[224:227], v[240:241] offset:3072 nt
	s_movk_i32 s0, 0x3fff
	v_cmp_lt_i32_e32 vcc, s0, v76
	s_and_saveexec_b64 s[0:1], vcc
	s_xor_b64 s[0:1], exec, s[0:1]
	s_cbranch_execz .LBB0_34
	v_readlane_b32 s4, v254, 5
	s_cmp_lg_u32 s4, -1
	s_cselect_b32 s10, s4, 0
	s_mov_b64 s[4:5], src_shared_base
	s_cselect_b32 s4, s5, 0
	v_mov_b32_e32 v35, s4
	v_readlane_b32 s4, v254, 6
	s_cmp_lg_u32 s4, -1
	v_mov_b32_e32 v34, s10
	s_cselect_b32 s4, s4, 0
	s_cselect_b32 s5, s5, 0
	flat_load_dword v0, v[34:35] sc0 sc1
	s_waitcnt vmcnt(0)
	v_mov_b32_e32 v34, s4
	v_mov_b32_e32 v35, s5
	flat_load_dword v34, v[34:35] sc0 sc1
	s_waitcnt vmcnt(0)
	v_mov_b32_e32 v83, v1
	s_waitcnt lgkmcnt(0)
	v_readfirstlane_b32 s4, v0
	v_add_u32_e32 v0, 0xffffc000, v76
	v_readfirstlane_b32 s5, v34
	v_lshlrev_b64 v[34:35], 12, v[0:1]
	s_nop 0
	v_lshl_add_u64 v[34:35], s[4:5], 0, v[34:35]
	v_lshl_add_u64 v[42:43], v[34:35], 0, v[82:83]
	s_mov_b64 s[4:5], 0xee00000
	v_add_co_u32_e32 v36, vcc, s49, v42
	v_lshl_add_u64 v[34:35], v[42:43], 0, s[4:5]
	s_nop 0
	v_addc_co_u32_e32 v37, vcc, 0, v43, vcc
	s_mov_b32 s4, 0xef00000
	v_add_co_u32_e32 v44, vcc, s4, v42
	s_mov_b32 s4, 0xf000000
	s_nop 0
	v_addc_co_u32_e32 v45, vcc, 0, v43, vcc
	flat_load_dwordx4 v[38:41], v[36:37]
	flat_load_dwordx4 v[48:51], v[44:45]
	v_add_co_u32_e32 v36, vcc, s4, v42
	s_mov_b32 s4, 0xf100000
	s_nop 0
	v_addc_co_u32_e32 v37, vcc, 0, v43, vcc
	flat_load_dwordx4 v[52:55], v[36:37]
	s_waitcnt vmcnt(0) lgkmcnt(0)
	v_pk_add_f32 v[38:39], v[38:39], v[48:49]
	v_pk_add_f32 v[40:41], v[40:41], v[50:51]
	v_pk_add_f32 v[46:47], v[38:39], v[52:53]
	v_add_co_u32_e32 v38, vcc, s4, v42
	s_mov_b32 s4, 0xf200000
	s_nop 0
	v_addc_co_u32_e32 v39, vcc, 0, v43, vcc
	flat_load_dwordx4 v[56:59], v[38:39]
	v_add_co_u32_e32 v48, vcc, s4, v42
	s_mov_b32 s4, 0xf300000
	s_nop 0
	v_addc_co_u32_e32 v49, vcc, 0, v43, vcc
	flat_load_dwordx4 v[60:63], v[48:49]
	v_add_co_u32_e32 v52, vcc, s4, v42
	s_mov_b32 s4, 0xf400000
	s_nop 0
	v_addc_co_u32_e32 v53, vcc, 0, v43, vcc
	flat_load_dwordx4 v[64:67], v[52:53]
	v_pk_add_f32 v[40:41], v[40:41], v[54:55]
	s_waitcnt vmcnt(0) lgkmcnt(0)
	v_pk_add_f32 v[46:47], v[46:47], v[56:57]
	v_add_co_u32_e32 v56, vcc, s4, v42
	s_mov_b32 s4, 0xf500000
	s_nop 0
	v_addc_co_u32_e32 v57, vcc, 0, v43, vcc
	v_pk_add_f32 v[46:47], v[46:47], v[60:61]
	flat_load_dwordx4 v[68:71], v[56:57]
	v_add_co_u32_e32 v60, vcc, s4, v42
	s_mov_b32 s4, 0xf600000
	s_nop 0
	v_addc_co_u32_e32 v61, vcc, 0, v43, vcc
	flat_load_dwordx4 v[72:75], v[60:61]
	v_pk_add_f32 v[46:47], v[46:47], v[64:65]
	v_add_co_u32_e32 v64, vcc, s4, v42
	s_mov_b32 s4, 0xf700000
	s_nop 0
	v_addc_co_u32_e32 v65, vcc, 0, v43, vcc
	flat_load_dwordx4 v[84:87], v[64:65]
	v_pk_add_f32 v[40:41], v[40:41], v[58:59]
	s_waitcnt vmcnt(0) lgkmcnt(0)
	v_pk_add_f32 v[46:47], v[46:47], v[68:69]
	v_add_co_u32_e32 v68, vcc, s4, v42
	s_mov_b32 s4, 0xf800000
	s_nop 0
	v_addc_co_u32_e32 v69, vcc, 0, v43, vcc
	v_pk_add_f32 v[46:47], v[46:47], v[72:73]
	v_add_co_u32_e32 v72, vcc, s4, v42
	flat_load_dwordx4 v[88:91], v[68:69]
	s_nop 0
	v_addc_co_u32_e32 v73, vcc, 0, v43, vcc
	flat_load_dwordx4 v[92:95], v[72:73]
	v_pk_add_f32 v[40:41], v[40:41], v[62:63]
	v_pk_add_f32 v[46:47], v[46:47], v[84:85]
	v_pk_add_f32 v[40:41], v[40:41], v[66:67]
	s_waitcnt vmcnt(0) lgkmcnt(0)
	v_pk_add_f32 v[46:47], v[46:47], v[88:89]
	v_pk_add_f32 v[40:41], v[40:41], v[70:71]
	s_nop 0
	v_pk_add_f32 v[40:41], v[40:41], v[74:75]
	s_nop 0
	v_pk_add_f32 v[40:41], v[40:41], v[86:87]
	v_pk_add_f32 v[86:87], v[46:47], v[92:93]
	v_pk_add_f32 v[40:41], v[40:41], v[90:91]
	s_nop 0
	v_pk_add_f32 v[84:85], v[40:41], v[94:95]
	flat_load_dwordx4 v[40:43], v[34:35] offset:1024
	flat_load_dwordx4 v[88:91], v[44:45] offset:1024
	flat_load_dwordx4 v[92:95], v[36:37] offset:1024
	flat_load_dwordx4 v[102:105], v[38:39] offset:1024
	flat_load_dwordx4 v[106:109], v[48:49] offset:1024
	flat_load_dwordx4 v[110:113], v[52:53] offset:1024
	flat_load_dwordx4 v[114:117], v[56:57] offset:1024
	flat_load_dwordx4 v[118:121], v[60:61] offset:1024
	flat_load_dwordx4 v[122:125], v[64:65] offset:1024
	flat_load_dwordx4 v[126:129], v[68:69] offset:1024
	flat_load_dwordx4 v[130:133], v[72:73] offset:1024
	s_waitcnt vmcnt(0) lgkmcnt(0)
; template <int MODE>
; __device__ __forceinline__ void phase_rows(const PRef& p, const float* __restrict__ vsrc, const float* __restrict__ g1, const float* __restrict__ g2, float coef, int nsplit) {
;     ...
;         for (int k = 1; k < nsplit; ++k) {
; #pragma unroll
;           for (int i = 0; i < 4; ++i) { float4 t = ps[(size_t)k * (MS * DM / 4) + lane + 64 * i]; v[i].x += t.x; v[i].y += t.y; v[i].z += t.z; v[i].w += t.w; }
	v_pk_add_f32 v[40:41], v[40:41], v[88:89]
	v_pk_add_f32 v[42:43], v[42:43], v[90:91]
	v_pk_add_f32 v[40:41], v[40:41], v[92:93]
	v_pk_add_f32 v[42:43], v[42:43], v[94:95]
	v_pk_add_f32 v[40:41], v[40:41], v[102:103]
	v_pk_add_f32 v[42:43], v[42:43], v[104:105]
	v_pk_add_f32 v[40:41], v[40:41], v[106:107]
	v_pk_add_f32 v[42:43], v[42:43], v[108:109]
	v_pk_add_f32 v[40:41], v[40:41], v[110:111]
	v_pk_add_f32 v[42:43], v[42:43], v[112:113]
	v_pk_add_f32 v[40:41], v[40:41], v[114:115]
	v_pk_add_f32 v[42:43], v[42:43], v[116:117]
	v_pk_add_f32 v[40:41], v[40:41], v[118:119]
	v_pk_add_f32 v[42:43], v[42:43], v[120:121]
	v_pk_add_f32 v[40:41], v[40:41], v[122:123]
	v_pk_add_f32 v[42:43], v[42:43], v[124:125]
	v_pk_add_f32 v[40:41], v[40:41], v[126:127]
	v_pk_add_f32 v[42:43], v[42:43], v[128:129]
	v_pk_add_f32 v[90:91], v[40:41], v[130:131]
	v_pk_add_f32 v[88:89], v[42:43], v[132:133]
	flat_load_dwordx4 v[40:43], v[34:35] offset:2048
	flat_load_dwordx4 v[92:95], v[44:45] offset:2048
	flat_load_dwordx4 v[102:105], v[36:37] offset:2048
	flat_load_dwordx4 v[106:109], v[38:39] offset:2048
	flat_load_dwordx4 v[110:113], v[48:49] offset:2048
	flat_load_dwordx4 v[114:117], v[52:53] offset:2048
	flat_load_dwordx4 v[118:121], v[56:57] offset:2048
	flat_load_dwordx4 v[122:125], v[60:61] offset:2048
	flat_load_dwordx4 v[126:129], v[64:65] offset:2048
	flat_load_dwordx4 v[130:133], v[68:69] offset:2048
	flat_load_dwordx4 v[134:137], v[72:73] offset:2048
	s_waitcnt vmcnt(0) lgkmcnt(0)
	v_pk_add_f32 v[40:41], v[40:41], v[92:93]
	v_pk_add_f32 v[42:43], v[42:43], v[94:95]
	v_pk_add_f32 v[40:41], v[40:41], v[102:103]
	v_pk_add_f32 v[42:43], v[42:43], v[104:105]
	v_pk_add_f32 v[40:41], v[40:41], v[106:107]
	v_pk_add_f32 v[42:43], v[42:43], v[108:109]
	v_pk_add_f32 v[40:41], v[40:41], v[110:111]
	v_pk_add_f32 v[42:43], v[42:43], v[112:113]
	v_pk_add_f32 v[40:41], v[40:41], v[114:115]
	v_pk_add_f32 v[42:43], v[42:43], v[116:117]
	v_pk_add_f32 v[40:41], v[40:41], v[118:119]
	v_pk_add_f32 v[42:43], v[42:43], v[120:121]
	v_pk_add_f32 v[40:41], v[40:41], v[122:123]
	v_pk_add_f32 v[42:43], v[42:43], v[124:125]
	v_pk_add_f32 v[40:41], v[40:41], v[126:127]
	v_pk_add_f32 v[42:43], v[42:43], v[128:129]
	v_pk_add_f32 v[40:41], v[40:41], v[130:131]
	v_pk_add_f32 v[42:43], v[42:43], v[132:133]
	v_pk_add_f32 v[94:95], v[40:41], v[134:135]
	v_pk_add_f32 v[92:93], v[42:43], v[136:137]
	flat_load_dwordx4 v[40:43], v[34:35] offset:3072
	s_nop 0
	flat_load_dwordx4 v[44:47], v[44:45] offset:3072
	s_waitcnt vmcnt(0) lgkmcnt(0)
	v_pk_add_f32 v[40:41], v[40:41], v[44:45]
	flat_load_dwordx4 v[34:37], v[36:37] offset:3072
	s_nop 0
	flat_load_dwordx4 v[48:51], v[48:49] offset:3072
	s_waitcnt vmcnt(0) lgkmcnt(0)
	v_pk_add_f32 v[34:35], v[40:41], v[34:35]
	flat_load_dwordx4 v[38:41], v[38:39] offset:3072
	s_nop 0
	flat_load_dwordx4 v[52:55], v[52:53] offset:3072
	s_waitcnt vmcnt(0) lgkmcnt(0)
	v_pk_add_f32 v[34:35], v[34:35], v[38:39]
	flat_load_dwordx4 v[56:59], v[56:57] offset:3072
	v_pk_add_f32 v[38:39], v[42:43], v[46:47]
	flat_load_dwordx4 v[60:63], v[60:61] offset:3072
	v_pk_add_f32 v[36:37], v[38:39], v[36:37]
	flat_load_dwordx4 v[64:67], v[64:65] offset:3072
	v_pk_add_f32 v[36:37], v[36:37], v[40:41]
	flat_load_dwordx4 v[68:71], v[68:69] offset:3072
	v_pk_add_f32 v[34:35], v[34:35], v[48:49]
	flat_load_dwordx4 v[72:75], v[72:73] offset:3072
	v_pk_add_f32 v[36:37], v[36:37], v[50:51]
	v_pk_add_f32 v[34:35], v[34:35], v[52:53]
	v_pk_add_f32 v[36:37], v[36:37], v[54:55]
	s_waitcnt vmcnt(0) lgkmcnt(0)
	v_pk_add_f32 v[34:35], v[34:35], v[56:57]
	v_pk_add_f32 v[36:37], v[36:37], v[58:59]
	v_pk_add_f32 v[34:35], v[34:35], v[60:61]
	v_pk_add_f32 v[36:37], v[36:37], v[62:63]
	v_pk_add_f32 v[34:35], v[34:35], v[64:65]
	v_pk_add_f32 v[36:37], v[36:37], v[66:67]
	v_pk_add_f32 v[34:35], v[34:35], v[68:69]
	v_pk_add_f32 v[36:37], v[36:37], v[70:71]
	v_pk_add_f32 v[44:45], v[34:35], v[72:73]
	v_pk_add_f32 v[42:43], v[36:37], v[74:75]

;   __device__ __forceinline__ const float* in(int i) const { return reinterpret_cast<const float*>(ld64(i * 8)); }
;   __device__ __forceinline__ float* out() const { return reinterpret_cast<float*>(ld64(26 * 8)); }
;   __device__ __forceinline__ unsigned char* ws() const { return reinterpret_cast<unsigned char*>(ld64(27 * 8)); }
; __device__ __forceinline__ int opaque_tid() { int t = threadIdx.x; asm volatile("" : "+v"(t)); return t; }
; template <int MODE>
; __device__ __forceinline__ void phase_rows(const PRef& p, const float* __restrict__ vsrc, const float* __restrict__ g1, const float* __restrict__ g2, float coef, int nsplit) {
;   const int tidx = opaque_tid();
;   const int lane = tidx & 63, wave = tidx >> 6;
;   bf16* xn = (bf16*)(p.ws() + WS_XN);
;   float* hbuf = p.out() + O_Y;
;   const float* xp = p.in(0); const float* xs_ = p.in(1);
;   for (int row = blockIdx.x * 8 + wave; row < MT; row += gridDim.x * 8) {
;     ...
;       float4 g = reinterpret_cast<const float4*>(g2)[lane + 64 * i];
.LBB0_41:
	s_mov_b64 s[0:1], src_shared_base
	v_readlane_b32 s0, v254, 5
	s_cmp_lg_u32 s0, -1
	s_cselect_b32 s4, s0, 0
	v_readlane_b32 s0, v254, 6
	s_cselect_b32 s5, s1, 0
	s_cmp_lg_u32 s0, -1
	v_mov_b64_e32 v[2:3], s[4:5]
	s_cselect_b32 s4, s0, 0
	s_cselect_b32 s5, s1, 0
	s_add_i32 s0, 0, 0x23f98
	s_cmp_lg_u32 s0, -1
	s_cselect_b32 s0, s0, 0
	v_mov_b64_e32 v[4:5], s[4:5]
	s_cselect_b32 s4, s1, 0
	v_mov_b32_e32 v6, s0
	s_add_i32 s0, 0, 0x23f9c
	s_cmp_lg_u32 s0, -1
	v_mov_b32_e32 v7, s4
	s_cselect_b32 s0, s0, 0
	flat_load_dword v8, v[2:3] sc0 sc1
	s_waitcnt vmcnt(0)
	flat_load_dword v9, v[4:5] sc0 sc1
	s_waitcnt vmcnt(0)
	flat_load_dword v10, v[6:7] sc0 sc1
	s_waitcnt vmcnt(0)
	s_cselect_b32 s4, s1, 0
	v_mov_b32_e32 v6, s0
	s_add_i32 s0, 0, 0x23fa0
	s_cmp_lg_u32 s0, -1
	v_mov_b32_e32 v7, s4
	s_cselect_b32 s0, s0, 0
	flat_load_dword v11, v[6:7] sc0 sc1
	s_waitcnt vmcnt(0)
	s_cselect_b32 s4, s1, 0
	v_mov_b32_e32 v6, s0
	s_add_i32 s0, 0, 0x23fa4
	s_cmp_lg_u32 s0, -1
	v_mov_b32_e32 v7, s4
	s_cselect_b32 s0, s0, 0
	flat_load_dword v12, v[6:7] sc0 sc1
	s_waitcnt vmcnt(0)
	s_cselect_b32 s4, s1, 0
	v_mov_b32_e32 v6, s0
	s_add_i32 s0, 0, 0x23fd0
	s_cmp_lg_u32 s0, -1
	v_mov_b32_e32 v7, s4
	v_mov_b32_e32 v0, v171
	s_cselect_b32 s0, s0, 0
	flat_load_dword v6, v[6:7] sc0 sc1
	s_waitcnt vmcnt(0)
	flat_load_dword v7, v[2:3] sc0 sc1
	s_waitcnt vmcnt(0)
	flat_load_dword v4, v[4:5] sc0 sc1
	s_waitcnt vmcnt(0)
	s_cselect_b32 s4, s1, 0
	v_mov_b32_e32 v2, s0
	s_add_i32 s0, 0, 0x23fd4
	s_cmp_lg_u32 s0, -1
	v_mov_b32_e32 v3, s4
	s_cselect_b32 s0, s0, 0
	flat_load_dword v5, v[2:3] sc0 sc1
	s_waitcnt vmcnt(0)
	s_cselect_b32 s4, s1, 0
	v_mov_b32_e32 v2, s0
	s_add_i32 s0, 0, 0x23f00
	s_cmp_lg_u32 s0, -1
	v_mov_b32_e32 v3, s4
	s_cselect_b32 s0, s0, 0
	flat_load_dword v13, v[2:3] sc0 sc1
	s_waitcnt vmcnt(0)
	s_cselect_b32 s4, s1, 0
	v_mov_b32_e32 v2, s0
	s_add_i32 s0, 0, 0x23f04
	v_mov_b32_e32 v3, s4
	s_cmp_lg_u32 s0, -1
	flat_load_dword v2, v[2:3] sc0 sc1
	s_waitcnt vmcnt(0)
	s_cselect_b32 s0, s0, 0
	s_cselect_b32 s4, s1, 0
	s_waitcnt lgkmcnt(0)
	v_mov_b32_e32 v2, s0
	s_add_i32 s0, 0, 0x23f08
	v_mov_b32_e32 v3, s4
	s_cmp_lg_u32 s0, -1
	flat_load_dword v2, v[2:3] sc0 sc1
	s_waitcnt vmcnt(0)
	s_cselect_b32 s0, s0, 0
	s_cselect_b32 s4, s1, 0
	s_waitcnt lgkmcnt(0)
	v_mov_b32_e32 v2, s0
	s_add_i32 s0, 0, 0x23f0c
	v_mov_b32_e32 v3, s4
	s_cmp_lg_u32 s0, -1
	flat_load_dword v2, v[2:3] sc0 sc1
	s_waitcnt vmcnt(0)
	s_cselect_b32 s0, s0, 0
	s_cselect_b32 s1, s1, 0
	s_waitcnt lgkmcnt(0)
	v_mov_b32_e32 v2, s0
	v_mov_b32_e32 v3, s1
	flat_load_dword v2, v[2:3] sc0 sc1
	s_waitcnt vmcnt(0) lgkmcnt(0)
	v_ashrrev_i32_e32 v2, 6, v0
	v_readlane_b32 s4, v254, 42
	v_readfirstlane_b32 s0, v8
	s_nop 0
	v_add_u32_e32 v38, s4, v2
	s_movk_i32 s4, 0x4100
	v_readfirstlane_b32 s1, v9
	v_readfirstlane_b32 s12, v10
	v_cmp_gt_i32_e32 vcc, s4, v38
	v_readfirstlane_b32 s13, v11
	v_readfirstlane_b32 s14, v12
	v_readfirstlane_b32 s15, v6
	v_readfirstlane_b32 s6, v7
	v_readfirstlane_b32 s7, v4
	v_readfirstlane_b32 s10, v5
	v_readfirstlane_b32 s11, v13
	s_and_saveexec_b64 s[4:5], vcc
	s_cbranch_execz .LBB0_48
	v_and_b32_e32 v22, 63, v0
	v_lshlrev_b32_e32 v0, 4, v22
	v_lshl_add_u64 v[40:41], s[14:15], 0, v[0:1]
	v_lshl_add_u64 v[18:19], s[12:13], 0, v[0:1]
	flat_load_dwordx4 v[2:5], v[40:41]
	flat_load_dwordx4 v[72:75], v[40:41] offset:1024
	flat_load_dwordx4 v[76:79], v[40:41] offset:2048
	flat_load_dwordx4 v[80:83], v[40:41] offset:3072
	flat_load_dwordx4 v[6:9], v[18:19]
	flat_load_dwordx4 v[10:13], v[18:19] offset:1024
	flat_load_dwordx4 v[14:17], v[18:19] offset:2048
	s_nop 0
	flat_load_dwordx4 v[18:21], v[18:19] offset:3072
	v_xor_b32_e32 v23, 32, v193
	v_cmp_lt_i32_e32 vcc, v23, v195
	v_lshl_add_u64 v[42:43], s[10:11], 0, v[0:1]
	v_lshlrev_b32_e32 v0, 3, v22
	v_cndmask_b32_e32 v23, v193, v23, vcc
	v_cmp_lt_i32_e32 vcc, v253, v195
	v_lshlrev_b32_e32 v58, 2, v23
	v_lshl_add_u64 v[24:25], s[0:1], 0, v[0:1]
	v_cndmask_b32_e32 v23, v193, v253, vcc
	v_cmp_lt_i32_e32 vcc, v210, v195
	v_lshlrev_b32_e32 v59, 2, v23
	s_mov_b64 s[0:1], 0x4b00000
	v_cndmask_b32_e32 v23, v193, v210, vcc
	v_lshlrev_b32_e32 v60, 2, v23
	v_xor_b32_e32 v23, 4, v193
	v_cmp_lt_i32_e32 vcc, v23, v195
	v_lshl_add_u64 v[44:45], v[24:25], 0, s[0:1]
	v_lshl_add_u64 v[24:25], s[6:7], 0, v[0:1]
	v_cndmask_b32_e32 v23, v193, v23, vcc
	v_lshlrev_b32_e32 v61, 2, v23
	v_xor_b32_e32 v23, 2, v193
	v_cmp_lt_i32_e32 vcc, v23, v195
	s_mov_b64 s[0:1], 0x2a00000
	v_lshl_add_u64 v[46:47], v[24:25], 0, s[0:1]
	v_cndmask_b32_e32 v23, v193, v23, vcc
	v_lshlrev_b32_e32 v62, 2, v23
	v_xor_b32_e32 v23, 1, v193
	v_cmp_lt_i32_e32 vcc, v23, v195
	s_mov_b64 s[6:7], 0
	v_lshlrev_b32_e32 v48, 4, v22
	v_cndmask_b32_e32 v23, v193, v23, vcc
	v_lshlrev_b32_e32 v63, 2, v23
	s_branch .LBB0_44
; template <int MODE>
; __device__ __forceinline__ void phase_rows(const PRef& p, const float* __restrict__ vsrc, const float* __restrict__ g1, const float* __restrict__ g2, float coef, int nsplit) {
;     ...
; #pragma unroll
;       for (int i = 0; i < 4; ++i) ss += v[i].x * v[i].x + v[i].y * v[i].y + v[i].z * v[i].z + v[i].w * v[i].w;
;       ss = wave_sum(ss);
;       const float r = rsqrtf(ss * (1.f / DM) + RMS_EPS) * coef;
; #pragma unroll
;       for (int i = 0; i < 4; ++i) {
;         const f32x4v bt = __builtin_nontemporal_load(reinterpret_cast<const f32x4v*>(bs) + lane + 64 * i); const float4 b = make_float4(bt[0], bt[1], bt[2], bt[3]);
;         float4 g = reinterpret_cast<const float4*>(g1)[lane + 64 * i];
;         h[i].x = b.x + v[i].x * r * g.x; h[i].y = b.y + v[i].y * r * g.y; h[i].z = b.z + v[i].z * r * g.z; h[i].w = b.w + v[i].w * r * g.w;
;       }
;       if (MODE != 3) {
;         float4* hd = reinterpret_cast<float4*>(hbuf + (size_t)row * DM);
; #pragma unroll
;         for (int i = 0; i < 4; ++i) __builtin_nontemporal_store(f32x4v{h[i].x, h[i].y, h[i].z, h[i].w}, reinterpret_cast<f32x4v*>(hd) + lane + 64 * i);
;       }
;     }
;     float ss2 = 0.f;
; #pragma unroll
;     for (int i = 0; i < 4; ++i) ss2 += h[i].x * h[i].x + h[i].y * h[i].y + h[i].z * h[i].z + h[i].w * h[i].w;
;     ss2 = wave_sum(ss2);
;     const float r2 = rsqrtf(ss2 * (1.f / DM) + RMS_EPS);
; #pragma unroll
;     for (int i = 0; i < 4; ++i) {
;       float4 g = reinterpret_cast<const float4*>(g2)[lane + 64 * i];
;       float o0 = h[i].x * r2 * g.x, o1 = h[i].y * r2 * g.y, o2 = h[i].z * r2 * g.z, o3 = h[i].w * r2 * g.w;
;       if (MODE == 3) {
;         __builtin_nontemporal_store(f32x4v{o0, o1, o2, o3}, reinterpret_cast<f32x4v*>(hbuf + (size_t)row * DM) + lane + 64 * i);
;       } else {
;         u32x2 w = {cvtpk(o0, o1), cvtpk(o2, o3)};
;         reinterpret_cast<u32x2*>(xn + (size_t)row * DM)[lane + 64 * i] = w;
;       }
;     }
.LBB0_43:
	s_or_b64 exec, exec, s[0:1]
	v_mov_b32_e32 v30, v26
	v_mov_b32_e32 v31, v22
	v_pk_mul_f32 v[30:31], v[30:31], v[30:31]
	v_mov_b32_e32 v32, v27
	v_mov_b32_e32 v33, v23
	v_pk_fma_f32 v[30:31], v[32:33], v[32:33], v[30:31]
	v_mov_b32_e32 v32, v28
	v_mov_b32_e32 v33, v24
	v_pk_fma_f32 v[30:31], v[32:33], v[32:33], v[30:31]
	v_mov_b32_e32 v32, v29
	v_mov_b32_e32 v33, v25
	v_pk_fma_f32 v[30:31], v[32:33], v[32:33], v[30:31]
	v_mov_b32_e32 v32, v34
	v_mov_b32_e32 v33, v52
	v_pk_mul_f32 v[32:33], v[32:33], v[32:33]
	v_mov_b32_e32 v56, v35
	v_mov_b32_e32 v57, v53
	v_pk_fma_f32 v[32:33], v[56:57], v[56:57], v[32:33]
	v_mov_b32_e32 v56, v36
	v_mov_b32_e32 v57, v54
	v_pk_fma_f32 v[32:33], v[56:57], v[56:57], v[32:33]
	v_mov_b32_e32 v56, v37
	v_mov_b32_e32 v57, v55
	v_pk_fma_f32 v[32:33], v[56:57], v[56:57], v[32:33]
	v_add_f32_e32 v0, v30, v31
	v_add_f32_e32 v0, v33, v0
	v_add_f32_e32 v0, v32, v0
	ds_bpermute_b32 v30, v58, v0
	s_mov_b32 s0, 0x800000
	v_lshl_add_u64 v[56:57], v[50:51], 2, v[42:43]
	v_lshl_add_u64 v[50:51], v[50:51], 1, v[46:47]
	s_waitcnt lgkmcnt(0)
	v_add_f32_e32 v0, v0, v30
	ds_bpermute_b32 v30, v59, v0
	s_waitcnt lgkmcnt(0)
	v_add_f32_e32 v0, v0, v30
	ds_bpermute_b32 v30, v60, v0
	s_waitcnt lgkmcnt(0)
	v_add_f32_e32 v0, v0, v30
	ds_bpermute_b32 v30, v61, v0
	s_waitcnt lgkmcnt(0)
	v_add_f32_e32 v0, v0, v30
	ds_bpermute_b32 v30, v62, v0
	s_waitcnt lgkmcnt(0)
	v_add_f32_e32 v0, v0, v30
	ds_bpermute_b32 v30, v63, v0
	s_waitcnt lgkmcnt(0)
	v_add_f32_e32 v0, v0, v30
	v_fmamk_f32 v0, v0, 0x3a800000, v190
	v_cmp_gt_f32_e32 vcc, s0, v0
	v_mul_f32_e32 v30, 0x4b800000, v0
	s_nop 0
	v_cndmask_b32_e32 v0, v0, v30, vcc
	v_rsq_f32_e32 v0, v0
	s_nop 0
	v_mul_f32_e32 v30, 0x45800000, v0
	v_cndmask_b32_e32 v0, v0, v30, vcc
	v_pk_mul_f32 v[22:23], v[22:23], v[0:1] op_sel_hi:[1,0]
	v_pk_mul_f32 v[26:27], v[26:27], v[0:1] op_sel_hi:[1,0]
	v_pk_mul_f32 v[52:53], v[52:53], v[0:1] op_sel_hi:[1,0]
	v_pk_mul_f32 v[36:37], v[36:37], v[0:1] op_sel_hi:[1,0]
	v_pk_mul_f32 v[34:35], v[34:35], v[0:1] op_sel_hi:[1,0]
	s_waitcnt vmcnt(0) lgkmcnt(0)
	v_pk_fma_f32 v[30:31], v[6:7], v[22:23], v[84:85]
	v_pk_mul_f32 v[22:23], v[24:25], v[0:1] op_sel_hi:[1,0]
	s_nop 0
	v_pk_fma_f32 v[32:33], v[8:9], v[22:23], v[86:87]
	v_pk_fma_f32 v[26:27], v[10:11], v[26:27], v[88:89]
	v_pk_mul_f32 v[22:23], v[28:29], v[0:1] op_sel_hi:[1,0]
	s_nop 0
	v_pk_fma_f32 v[28:29], v[12:13], v[22:23], v[90:91]
	v_pk_fma_f32 v[22:23], v[14:15], v[52:53], v[92:93]
	v_pk_mul_f32 v[52:53], v[54:55], v[0:1] op_sel_hi:[1,0]
	s_nop 0
	v_pk_fma_f32 v[24:25], v[16:17], v[52:53], v[94:95]
	v_pk_fma_f32 v[36:37], v[20:21], v[36:37], v[98:99]
	v_mov_b32_e32 v54, v31
	v_mov_b32_e32 v55, v27
	v_pk_fma_f32 v[34:35], v[18:19], v[34:35], v[96:97]
	v_mov_b32_e32 v52, v30
	v_mov_b32_e32 v53, v26
	v_pk_mul_f32 v[54:55], v[54:55], v[54:55]
	flat_store_dwordx4 v[56:57], v[30:33] nt
	flat_store_dwordx4 v[56:57], v[26:29] offset:1024 nt
	flat_store_dwordx4 v[56:57], v[22:25] offset:2048 nt
	flat_store_dwordx4 v[56:57], v[34:37] offset:3072 nt
	v_pk_fma_f32 v[52:53], v[52:53], v[52:53], v[54:55]
	v_mov_b32_e32 v54, v32
	v_mov_b32_e32 v55, v28
	v_pk_fma_f32 v[52:53], v[54:55], v[54:55], v[52:53]
	v_mov_b32_e32 v54, v33
	v_mov_b32_e32 v55, v29
	v_mov_b32_e32 v56, v35
	v_mov_b32_e32 v57, v23
	v_pk_fma_f32 v[52:53], v[54:55], v[54:55], v[52:53]
	v_mov_b32_e32 v54, v34
	v_mov_b32_e32 v55, v22
	v_pk_mul_f32 v[56:57], v[56:57], v[56:57]
	v_add_f32_e32 v0, v52, v53
	v_pk_fma_f32 v[54:55], v[54:55], v[54:55], v[56:57]
	v_mov_b32_e32 v56, v36
	v_mov_b32_e32 v57, v24
	v_pk_fma_f32 v[54:55], v[56:57], v[56:57], v[54:55]
	v_mov_b32_e32 v56, v37
	v_mov_b32_e32 v57, v25
	v_pk_fma_f32 v[54:55], v[56:57], v[56:57], v[54:55]
	s_nop 0
	v_add_f32_e32 v0, v55, v0
	v_add_f32_e32 v0, v54, v0
	ds_bpermute_b32 v39, v58, v0
	s_waitcnt lgkmcnt(0)
	v_add_f32_e32 v0, v0, v39
	ds_bpermute_b32 v39, v59, v0
	s_waitcnt lgkmcnt(0)
	v_add_f32_e32 v0, v0, v39
	ds_bpermute_b32 v39, v60, v0
	s_waitcnt lgkmcnt(0)
	v_add_f32_e32 v0, v0, v39
	ds_bpermute_b32 v39, v61, v0
	s_waitcnt lgkmcnt(0)
	v_add_f32_e32 v0, v0, v39
	ds_bpermute_b32 v39, v62, v0
	s_waitcnt lgkmcnt(0)
	v_add_f32_e32 v0, v0, v39
	ds_bpermute_b32 v39, v63, v0
	s_waitcnt lgkmcnt(0)
	v_add_f32_e32 v0, v0, v39
	v_fmamk_f32 v0, v0, 0x3a800000, v190
	v_cmp_gt_f32_e32 vcc, s0, v0
	v_mul_f32_e32 v39, 0x4b800000, v0
	v_readlane_b32 s0, v254, 21
	v_cndmask_b32_e32 v0, v0, v39, vcc
	v_rsq_f32_e32 v0, v0
	v_add_u32_e32 v38, s0, v38
	s_movk_i32 s0, 0x40ff
	v_mul_f32_e32 v39, 0x45800000, v0
	v_cndmask_b32_e32 v0, v0, v39, vcc
	v_mul_f32_e32 v30, v30, v0
	v_mul_f32_e32 v31, v31, v0
	v_mul_f32_e32 v30, v2, v30
	v_mul_f32_e32 v31, v3, v31
	v_mul_f32_e32 v32, v32, v0
	v_mul_f32_e32 v33, v33, v0
	v_mul_f32_e32 v32, v4, v32
	v_mul_f32_e32 v33, v5, v33
	v_cvt_pk_bf16_f32 v30, v30, v31
	v_cvt_pk_bf16_f32 v31, v32, v33
	flat_store_dwordx2 v[50:51], v[30:31]
	v_mul_f32_e32 v26, v26, v0
	v_mul_f32_e32 v27, v27, v0
	v_mul_f32_e32 v28, v28, v0
	v_mul_f32_e32 v29, v29, v0
	v_mul_f32_e32 v22, v22, v0
	v_mul_f32_e32 v23, v23, v0
	v_mul_f32_e32 v24, v24, v0
	v_mul_f32_e32 v25, v25, v0
	v_cmp_lt_i32_e32 vcc, s0, v38
	s_or_b64 s[6:7], vcc, s[6:7]
	v_mul_f32_e32 v26, v72, v26
	v_mul_f32_e32 v27, v73, v27
	v_mul_f32_e32 v28, v74, v28
	v_mul_f32_e32 v29, v75, v29
	v_cvt_pk_bf16_f32 v26, v26, v27
	v_cvt_pk_bf16_f32 v27, v28, v29
	flat_store_dwordx2 v[50:51], v[26:27] offset:512
	v_mul_f32_e32 v22, v76, v22
	v_mul_f32_e32 v23, v77, v23
	v_mul_f32_e32 v24, v24, v78
	v_mul_f32_e32 v25, v25, v79
	v_cvt_pk_bf16_f32 v22, v22, v23
	v_cvt_pk_bf16_f32 v23, v24, v25
	flat_store_dwordx2 v[50:51], v[22:23] offset:1024
	v_mul_f32_e32 v26, v34, v0
	v_mul_f32_e32 v22, v26, v80
	v_mul_f32_e32 v26, v35, v0
	v_mul_f32_e32 v23, v26, v81
	v_mul_f32_e32 v26, v36, v0
	v_mul_f32_e32 v0, v37, v0
	v_mul_f32_e32 v24, v26, v82
	v_mul_f32_e32 v0, v0, v83
	v_cvt_pk_bf16_f32 v22, v22, v23
	v_cvt_pk_bf16_f32 v23, v24, v0
	flat_store_dwordx2 v[50:51], v[22:23] offset:1536
	s_andn2_b64 exec, exec, s[6:7]
	s_cbranch_execz .LBB0_48
;   __device__ __forceinline__ unsigned char* ws() const { return reinterpret_cast<unsigned char*>(ld64(27 * 8)); }
; template <int MODE>
; __device__ __forceinline__ void phase_rows(const PRef& p, const float* __restrict__ vsrc, const float* __restrict__ g1, const float* __restrict__ g2, float coef, int nsplit) {
;     ...
;       if (row < MP) {
; #pragma unroll
;         for (int i = 0; i < 4; ++i) { const u32x2 q = vs[lane + 64 * i];
;           v[i] = make_float4(__uint_as_float(q[0] << 16), __uint_as_float(q[0] & 0xffff0000u), __uint_as_float(q[1] << 16), __uint_as_float(q[1] & 0xffff0000u)); }
;       } else {
;         const float4* ps = reinterpret_cast<const float4*>((const float*)(p.ws() + WS_PART) + (size_t)(row - MP) * DM);
; #pragma unroll
;         for (int i = 0; i < 4; ++i) v[i] = ps[lane + 64 * i];
;         for (int k = 1; k < nsplit; ++k) {
; #pragma unroll
;           for (int i = 0; i < 4; ++i) { float4 t = ps[(size_t)k * (MS * DM / 4) + lane + 64 * i]; v[i].x += t.x; v[i].y += t.y; v[i].z += t.z; v[i].w += t.w; }
;     ...
;         const f32x4v bt = __builtin_nontemporal_load(reinterpret_cast<const f32x4v*>(bs) + lane + 64 * i); const float4 b = make_float4(bt[0], bt[1], bt[2], bt[3]);
.LBB0_44:
	v_ashrrev_i32_e32 v103, 31, v38
	v_mov_b32_e32 v102, v38
	v_lshlrev_b64 v[102:103], 10, v[102:103]
	v_lshl_add_u64 v[100:101], v[102:103], 2, v[42:43]
	flat_load_dwordx4 v[84:87], v[100:101] nt
	flat_load_dwordx4 v[88:91], v[100:101] offset:1024 nt
	flat_load_dwordx4 v[92:95], v[100:101] offset:2048 nt
	flat_load_dwordx4 v[96:99], v[100:101] offset:3072 nt
	s_movk_i32 s0, 0x3fff
	v_cmp_lt_i32_e32 vcc, s0, v38
	s_and_saveexec_b64 s[0:1], vcc
	s_xor_b64 s[0:1], exec, s[0:1]
	s_cbranch_execz .LBB0_46
	v_readlane_b32 s10, v254, 5
	s_cmp_lg_u32 s10, -1
	s_cselect_b32 s12, s10, 0
	s_mov_b64 s[10:11], src_shared_base
	s_cselect_b32 s10, s11, 0
	v_mov_b32_e32 v23, s10
	v_readlane_b32 s10, v254, 6
	s_cmp_lg_u32 s10, -1
	v_mov_b32_e32 v22, s12
	s_cselect_b32 s10, s10, 0
	s_cselect_b32 s11, s11, 0
	flat_load_dword v0, v[22:23] sc0 sc1
	s_waitcnt vmcnt(0)
	v_mov_b32_e32 v22, s10
	v_mov_b32_e32 v23, s11
	flat_load_dword v22, v[22:23] sc0 sc1
	s_waitcnt vmcnt(0)
	v_mov_b32_e32 v49, v1
	s_waitcnt lgkmcnt(0)
	v_readfirstlane_b32 s10, v0
	v_add_u32_e32 v0, 0xffffc000, v38
	v_readfirstlane_b32 s11, v22
	v_lshlrev_b64 v[22:23], 12, v[0:1]
	s_nop 0
	v_lshl_add_u64 v[22:23], s[10:11], 0, v[22:23]
	v_lshl_add_u64 v[34:35], v[22:23], 0, v[48:49]
	s_mov_b64 s[10:11], 0xee00000
	v_add_co_u32_e32 v22, vcc, s49, v34
	v_lshl_add_u64 v[64:65], v[34:35], 0, s[10:11]
	s_nop 0
	v_addc_co_u32_e32 v23, vcc, 0, v35, vcc
	s_mov_b32 s10, 0xef00000
	v_add_co_u32_e32 v66, vcc, s10, v34
	s_mov_b32 s10, 0xf000000
	s_nop 0
	v_addc_co_u32_e32 v67, vcc, 0, v35, vcc
	v_add_co_u32_e32 v68, vcc, s10, v34
	s_mov_b32 s10, 0xf100000
	s_nop 0
	v_addc_co_u32_e32 v69, vcc, 0, v35, vcc
	flat_load_dwordx4 v[22:25], v[22:23]
	v_add_co_u32_e32 v70, vcc, s10, v34
	flat_load_dwordx4 v[26:29], v[66:67]
	flat_load_dwordx4 v[30:33], v[68:69]
	v_addc_co_u32_e32 v71, vcc, 0, v35, vcc
	flat_load_dwordx4 v[34:37], v[70:71]
	s_waitcnt vmcnt(0) lgkmcnt(0)
	v_pk_add_f32 v[22:23], v[22:23], v[26:27]
	v_pk_add_f32 v[24:25], v[24:25], v[28:29]
	v_pk_add_f32 v[22:23], v[22:23], v[30:31]
	v_pk_add_f32 v[24:25], v[24:25], v[32:33]
	flat_load_dwordx4 v[26:29], v[64:65] offset:1024
	flat_load_dwordx4 v[30:33], v[66:67] offset:1024
	v_pk_add_f32 v[22:23], v[22:23], v[34:35]
	v_pk_add_f32 v[24:25], v[24:25], v[36:37]
	flat_load_dwordx4 v[34:37], v[68:69] offset:1024
	flat_load_dwordx4 v[50:53], v[70:71] offset:1024
	s_waitcnt vmcnt(0) lgkmcnt(0)
	v_pk_add_f32 v[26:27], v[26:27], v[30:31]
	v_pk_add_f32 v[28:29], v[28:29], v[32:33]
	v_pk_add_f32 v[26:27], v[26:27], v[34:35]
	v_pk_add_f32 v[28:29], v[28:29], v[36:37]
	flat_load_dwordx4 v[30:33], v[64:65] offset:2048
	flat_load_dwordx4 v[34:37], v[66:67] offset:2048
	v_pk_add_f32 v[26:27], v[26:27], v[50:51]
	v_pk_add_f32 v[28:29], v[28:29], v[52:53]
	flat_load_dwordx4 v[50:53], v[68:69] offset:2048
	flat_load_dwordx4 v[54:57], v[70:71] offset:2048
	s_waitcnt vmcnt(0) lgkmcnt(0)
	v_pk_add_f32 v[30:31], v[30:31], v[34:35]
	v_pk_add_f32 v[32:33], v[32:33], v[36:37]
	v_pk_add_f32 v[30:31], v[30:31], v[50:51]
	v_pk_add_f32 v[32:33], v[32:33], v[52:53]
	v_pk_add_f32 v[52:53], v[30:31], v[54:55]
	v_pk_add_f32 v[54:55], v[32:33], v[56:57]
	flat_load_dwordx4 v[30:33], v[64:65] offset:3072
	flat_load_dwordx4 v[34:37], v[66:67] offset:3072
	s_waitcnt vmcnt(0) lgkmcnt(0)
	v_pk_add_f32 v[30:31], v[30:31], v[34:35]
	flat_load_dwordx4 v[64:67], v[68:69] offset:3072
	v_pk_add_f32 v[32:33], v[32:33], v[36:37]
	flat_load_dwordx4 v[68:71], v[70:71] offset:3072
	s_waitcnt vmcnt(0) lgkmcnt(0)
	v_pk_add_f32 v[30:31], v[30:31], v[64:65]
	v_pk_add_f32 v[32:33], v[32:33], v[66:67]
	v_pk_add_f32 v[34:35], v[30:31], v[68:69]
	v_pk_add_f32 v[36:37], v[32:33], v[70:71]

; __device__ __forceinline__ void attn_diff(const bf16* __restrict__ Qg, const bf16* __restrict__ Kg, const bf16* __restrict__ Vg, int vts, ...
;     ...
;     __syncthreads();
;     {
;       int mx = dn[0];
; #pragma unroll
;       for (int i = 1; i < 8; ++i) mx = max(mx, dn[i]);
;       if (mx <= it) break;
;     }
.LBB0_214:
	s_or_b64 exec, exec, s[0:1]
	v_mov_b32_e32 v4, 0x22040
	s_waitcnt lgkmcnt(0)
	s_barrier
	ds_read_b128 v[8:11], v4 offset:16
	ds_read_b128 v[4:7], v4
	v_add_u32_e32 v239, 0x80, v239
	v_add_u32_e32 v240, 0x80, v240
	v_add_u32_e32 v241, 0xffffff80, v241
	s_andn2_b64 s[0:1], s[94:95], exec
	s_waitcnt lgkmcnt(0)
	v_max3_i32 v0, v4, v5, v6
	v_max3_i32 v3, v7, v8, v9
	v_max3_i32 v0, v0, v10, v11
	v_max_i32_e32 v0, v0, v3
	v_cmp_ge_i32_e32 vcc, s86, v0
	s_and_b64 s[10:11], vcc, exec
	s_or_b64 s[94:95], s[0:1], s[10:11]

;   __device__ __forceinline__ const float* in(int i) const { return reinterpret_cast<const float*>(ld64(i * 8)); }
;   __device__ __forceinline__ float* out() const { return reinterpret_cast<float*>(ld64(26 * 8)); }
;   __device__ __forceinline__ unsigned char* ws() const { return reinterpret_cast<unsigned char*>(ld64(27 * 8)); }
; __device__ __forceinline__ int opaque_tid() { int t = threadIdx.x; asm volatile("" : "+v"(t)); return t; }
; template <int MODE>
; __device__ __forceinline__ void phase_rows(const PRef& p, const float* __restrict__ vsrc, const float* __restrict__ g1, const float* __restrict__ g2, float coef, int nsplit) {
;   const int tidx = opaque_tid();
;   const int lane = tidx & 63, wave = tidx >> 6;
;   bf16* xn = (bf16*)(p.ws() + WS_XN);
;   float* hbuf = p.out() + O_Y;
;   const float* xp = p.in(0); const float* xs_ = p.in(1);
;   for (int row = blockIdx.x * 8 + wave; row < MT; row += gridDim.x * 8) {
;     ...
;       float4 g = reinterpret_cast<const float4*>(g2)[lane + 64 * i];
.LBB0_304:
	s_and_b64 vcc, exec, s[0:1]
	s_cbranch_vccz .LBB0_313
	v_readlane_b32 s0, v254, 5
	s_cmp_lg_u32 s0, -1
	s_mov_b64 s[12:13], src_shared_base
	s_cselect_b32 s0, s0, 0
	s_cselect_b32 s1, s13, 0
	v_mov_b64_e32 v[2:3], s[0:1]
	v_readlane_b32 s0, v254, 6
	s_cmp_lg_u32 s0, -1
	s_cselect_b32 s0, s0, 0
	s_cselect_b32 s1, s13, 0
	v_mov_b64_e32 v[4:5], s[0:1]
	flat_load_dword v0, v[2:3] sc0 sc1
	s_waitcnt vmcnt(0)
	flat_load_dword v6, v[4:5] sc0 sc1
	s_waitcnt vmcnt(0)
	s_add_i32 s4, 0, 0x23f50
	s_cmp_lg_u32 s4, -1
	s_cselect_b32 s4, s4, 0
	s_cselect_b32 s5, s13, 0
	v_mov_b32_e32 v7, s5
	s_waitcnt lgkmcnt(0)
	v_readfirstlane_b32 s0, v0
	v_readfirstlane_b32 s1, v6
	v_mov_b32_e32 v6, s4
	s_add_i32 s4, 0, 0x23f54
	s_cmp_lg_u32 s4, -1
	s_cselect_b32 s4, s4, 0
	s_cselect_b32 s5, s13, 0
	flat_load_dword v0, v[6:7] sc0 sc1
	s_waitcnt vmcnt(0)
	v_mov_b32_e32 v6, s4
	v_mov_b32_e32 v7, s5
	flat_load_dword v6, v[6:7] sc0 sc1
	s_waitcnt vmcnt(0)
	s_add_i32 s6, 0, 0x23f58
	s_cmp_lg_u32 s6, -1
	s_cselect_b32 s6, s6, 0
	s_cselect_b32 s7, s13, 0
	v_mov_b32_e32 v7, s7
	s_waitcnt lgkmcnt(0)
	v_readfirstlane_b32 s4, v0
	v_readfirstlane_b32 s5, v6
	v_mov_b32_e32 v6, s6
	flat_load_dword v0, v[6:7] sc0 sc1
	s_waitcnt vmcnt(0)
	s_add_i32 s6, 0, 0x23f5c
	s_cmp_lg_u32 s6, -1
	s_cselect_b32 s6, s6, 0
	s_cselect_b32 s7, s13, 0
	v_mov_b32_e32 v6, s6
	v_mov_b32_e32 v7, s7
	flat_load_dword v6, v[6:7] sc0 sc1
	s_waitcnt vmcnt(0)
	s_add_i32 s10, 0, 0x23fd0
	s_cmp_lg_u32 s10, -1
	s_cselect_b32 s10, s10, 0
	s_cselect_b32 s11, s13, 0
	s_waitcnt lgkmcnt(0)
	v_readfirstlane_b32 s16, v0
	v_mov_b32_e32 v0, v171
	flat_load_dword v2, v[2:3] sc0 sc1
	s_waitcnt vmcnt(0)
	flat_load_dword v3, v[4:5] sc0 sc1
	s_waitcnt vmcnt(0)
	v_readfirstlane_b32 s17, v6
	v_ashrrev_i32_e32 v6, 6, v0
	s_waitcnt lgkmcnt(0)
	v_readfirstlane_b32 s6, v2
	v_mov_b32_e32 v2, s10
	s_add_i32 s10, 0, 0x23fd4
	s_cmp_lg_u32 s10, -1
	v_readfirstlane_b32 s7, v3
	v_mov_b32_e32 v3, s11
	s_cselect_b32 s10, s10, 0
	s_cselect_b32 s11, s13, 0
	flat_load_dword v4, v[2:3] sc0 sc1
	s_waitcnt vmcnt(0)
	v_mov_b32_e32 v2, s10
	v_mov_b32_e32 v3, s11
	flat_load_dword v2, v[2:3] sc0 sc1
	s_waitcnt vmcnt(0)
	s_add_i32 s10, 0, 0x23f00
	s_cmp_lg_u32 s10, -1
	s_cselect_b32 s10, s10, 0
	s_cselect_b32 s11, s13, 0
	v_mov_b32_e32 v3, s11
	s_waitcnt lgkmcnt(0)
	v_readfirstlane_b32 s18, v4
	v_readfirstlane_b32 s19, v2
	v_mov_b32_e32 v2, s10
	s_add_i32 s10, 0, 0x23f04
	s_cmp_lg_u32 s10, -1
	s_cselect_b32 s10, s10, 0
	s_cselect_b32 s11, s13, 0
	flat_load_dword v4, v[2:3] sc0 sc1
	s_waitcnt vmcnt(0)
	v_mov_b32_e32 v2, s10
	v_mov_b32_e32 v3, s11
	flat_load_dword v2, v[2:3] sc0 sc1
	s_waitcnt vmcnt(0)
	s_add_i32 s12, 0, 0x23f08
	s_cmp_lg_u32 s12, -1
	s_cselect_b32 s12, s12, 0
	s_cselect_b32 s14, s13, 0
	v_mov_b32_e32 v3, s14
	v_readlane_b32 s14, v254, 42
	s_waitcnt lgkmcnt(0)
	v_readfirstlane_b32 s10, v4
	v_add_u32_e32 v58, s14, v6
	s_movk_i32 s14, 0x4100
	v_readfirstlane_b32 s11, v2
	v_mov_b32_e32 v2, s12
	s_add_i32 s12, 0, 0x23f0c
	s_cmp_lg_u32 s12, -1
	s_cselect_b32 s12, s12, 0
	s_cselect_b32 s13, s13, 0
	flat_load_dword v4, v[2:3] sc0 sc1
	s_waitcnt vmcnt(0)
	v_mov_b32_e32 v2, s12
	v_mov_b32_e32 v3, s13
	flat_load_dword v2, v[2:3] sc0 sc1
	s_waitcnt vmcnt(0)
	v_cmp_gt_i32_e32 vcc, s14, v58
	s_waitcnt lgkmcnt(0)
	v_readfirstlane_b32 s12, v4
	v_readfirstlane_b32 s13, v2
	s_and_saveexec_b64 s[14:15], vcc
	s_cbranch_execz .LBB0_312
	v_and_b32_e32 v60, 63, v0
	v_lshlrev_b32_e32 v0, 4, v60
	v_lshl_add_u64 v[62:63], s[16:17], 0, v[0:1]
	v_lshl_add_u64 v[18:19], s[4:5], 0, v[0:1]
	flat_load_dwordx4 v[2:5], v[62:63]
	flat_load_dwordx4 v[228:231], v[62:63] offset:1024
	flat_load_dwordx4 v[232:235], v[62:63] offset:2048
	flat_load_dwordx4 v[236:239], v[62:63] offset:3072
	flat_load_dwordx4 v[6:9], v[18:19]
	flat_load_dwordx4 v[10:13], v[18:19] offset:1024
	flat_load_dwordx4 v[14:17], v[18:19] offset:2048
	s_nop 0
	flat_load_dwordx4 v[18:21], v[18:19] offset:3072
	v_xor_b32_e32 v22, 32, v193
	v_cmp_lt_i32_e32 vcc, v22, v195
	v_lshl_add_u64 v[64:65], s[18:19], 0, v[0:1]
	v_lshlrev_b32_e32 v0, 3, v60
	v_cndmask_b32_e32 v22, v193, v22, vcc
	v_cmp_lt_i32_e32 vcc, v253, v195
	v_lshlrev_b32_e32 v61, 2, v22
	s_mov_b64 s[16:17], 0
	v_cndmask_b32_e32 v22, v193, v253, vcc
	v_cmp_lt_i32_e32 vcc, v210, v195
	v_lshlrev_b32_e32 v84, 2, v22
	s_nop 0
	v_cndmask_b32_e32 v22, v193, v210, vcc
	v_lshlrev_b32_e32 v85, 2, v22
	v_xor_b32_e32 v22, 4, v193
	v_cmp_lt_i32_e32 vcc, v22, v195
	s_nop 1
	v_cndmask_b32_e32 v22, v193, v22, vcc
	v_lshlrev_b32_e32 v86, 2, v22
	v_xor_b32_e32 v22, 2, v193
	v_cmp_lt_i32_e32 vcc, v22, v195
	s_nop 1
	v_cndmask_b32_e32 v22, v193, v22, vcc
	v_lshlrev_b32_e32 v87, 2, v22
	v_xor_b32_e32 v22, 1, v193
	v_cmp_lt_i32_e32 vcc, v22, v195
	s_nop 1
	v_cndmask_b32_e32 v22, v193, v22, vcc
	v_lshlrev_b32_e32 v88, 2, v22
	v_lshl_add_u64 v[22:23], s[0:1], 0, v[0:1]
	s_mov_b64 s[0:1], 0x4b00000
	v_lshl_add_u64 v[66:67], v[22:23], 0, s[0:1]
	v_lshl_add_u64 v[22:23], s[6:7], 0, v[0:1]
	s_mov_b64 s[0:1], 0x2a00000
	v_lshl_add_u64 v[68:69], v[22:23], 0, s[0:1]
	s_branch .LBB0_308
; template <int MODE>
; __device__ __forceinline__ void phase_rows(const PRef& p, const float* __restrict__ vsrc, const float* __restrict__ g1, const float* __restrict__ g2, float coef, int nsplit) {
;     ...
; #pragma unroll
;       for (int i = 0; i < 4; ++i) ss += v[i].x * v[i].x + v[i].y * v[i].y + v[i].z * v[i].z + v[i].w * v[i].w;
;       ss = wave_sum(ss);
;       const float r = rsqrtf(ss * (1.f / DM) + RMS_EPS) * coef;
; #pragma unroll
;       for (int i = 0; i < 4; ++i) {
;         const f32x4v bt = __builtin_nontemporal_load(reinterpret_cast<const f32x4v*>(bs) + lane + 64 * i); const float4 b = make_float4(bt[0], bt[1], bt[2], bt[3]);
;         float4 g = reinterpret_cast<const float4*>(g1)[lane + 64 * i];
;         h[i].x = b.x + v[i].x * r * g.x; h[i].y = b.y + v[i].y * r * g.y; h[i].z = b.z + v[i].z * r * g.z; h[i].w = b.w + v[i].w * r * g.w;
;       }
;       if (MODE != 3) {
;         float4* hd = reinterpret_cast<float4*>(hbuf + (size_t)row * DM);
; #pragma unroll
;         for (int i = 0; i < 4; ++i) __builtin_nontemporal_store(f32x4v{h[i].x, h[i].y, h[i].z, h[i].w}, reinterpret_cast<f32x4v*>(hd) + lane + 64 * i);
;       }
;     }
;     float ss2 = 0.f;
; #pragma unroll
;     for (int i = 0; i < 4; ++i) ss2 += h[i].x * h[i].x + h[i].y * h[i].y + h[i].z * h[i].z + h[i].w * h[i].w;
;     ss2 = wave_sum(ss2);
;     const float r2 = rsqrtf(ss2 * (1.f / DM) + RMS_EPS);
; #pragma unroll
;     for (int i = 0; i < 4; ++i) {
;       float4 g = reinterpret_cast<const float4*>(g2)[lane + 64 * i];
;       float o0 = h[i].x * r2 * g.x, o1 = h[i].y * r2 * g.y, o2 = h[i].z * r2 * g.z, o3 = h[i].w * r2 * g.w;
;       if (MODE == 3) {
;         __builtin_nontemporal_store(f32x4v{o0, o1, o2, o3}, reinterpret_cast<f32x4v*>(hbuf + (size_t)row * DM) + lane + 64 * i);
;       } else {
;         u32x2 w = {cvtpk(o0, o1), cvtpk(o2, o3)};
;         reinterpret_cast<u32x2*>(xn + (size_t)row * DM)[lane + 64 * i] = w;
;       }
;     }
.LBB0_307:
	s_or_b64 exec, exec, s[0:1]
	v_lshlrev_b64 v[40:41], 2, v[38:39]
	v_lshl_add_u64 v[22:23], s[10:11], 0, v[40:41]
	v_lshl_add_u64 v[24:25], s[12:13], 0, v[74:75]
	v_cndmask_b32_e32 v23, v25, v23, vcc
	v_cndmask_b32_e32 v22, v24, v22, vcc
	v_mov_b32_e32 v24, v76
	v_mov_b32_e32 v25, v70
	v_pk_mul_f32 v[24:25], v[24:25], v[24:25]
	v_mov_b32_e32 v26, v77
	v_mov_b32_e32 v27, v71
	v_pk_fma_f32 v[24:25], v[26:27], v[26:27], v[24:25]
	v_mov_b32_e32 v26, v78
	v_mov_b32_e32 v27, v72
	v_pk_fma_f32 v[24:25], v[26:27], v[26:27], v[24:25]
	v_mov_b32_e32 v26, v79
	v_mov_b32_e32 v27, v73
	v_pk_fma_f32 v[24:25], v[26:27], v[26:27], v[24:25]
	v_mov_b32_e32 v26, v34
	v_mov_b32_e32 v27, v80
	v_pk_mul_f32 v[26:27], v[26:27], v[26:27]
	v_mov_b32_e32 v28, v35
	v_mov_b32_e32 v29, v81
	v_pk_fma_f32 v[26:27], v[28:29], v[28:29], v[26:27]
	v_mov_b32_e32 v28, v36
	v_mov_b32_e32 v29, v82
	v_pk_fma_f32 v[26:27], v[28:29], v[28:29], v[26:27]
	v_mov_b32_e32 v28, v37
	v_mov_b32_e32 v29, v83
	v_pk_fma_f32 v[26:27], v[28:29], v[28:29], v[26:27]
	v_add_f32_e32 v24, v24, v25
	v_add_f32_e32 v24, v27, v24
	v_add_f32_e32 v24, v26, v24
	ds_bpermute_b32 v25, v61, v24
	s_mov_b32 s0, 0x800000
	v_lshl_add_u64 v[44:45], v[22:23], 0, v[0:1]
	v_lshl_add_u64 v[40:41], v[64:65], 0, v[40:41]
	v_lshl_add_u64 v[38:39], v[38:39], 1, v[68:69]
	s_waitcnt lgkmcnt(0)
	v_add_f32_e32 v24, v24, v25
	ds_bpermute_b32 v25, v84, v24
	s_waitcnt lgkmcnt(0)
	v_add_f32_e32 v24, v24, v25
	ds_bpermute_b32 v25, v85, v24
	s_waitcnt lgkmcnt(0)
	v_add_f32_e32 v24, v24, v25
	ds_bpermute_b32 v25, v86, v24
	s_waitcnt lgkmcnt(0)
	v_add_f32_e32 v24, v24, v25
	ds_bpermute_b32 v25, v87, v24
	s_waitcnt lgkmcnt(0)
	v_add_f32_e32 v24, v24, v25
	ds_bpermute_b32 v25, v88, v24
	s_waitcnt lgkmcnt(0)
	v_add_f32_e32 v24, v24, v25
	v_fmamk_f32 v24, v24, 0x3a800000, v190
	v_cmp_gt_f32_e32 vcc, s0, v24
	v_mul_f32_e32 v25, 0x4b800000, v24
	s_nop 0
	v_cndmask_b32_e32 v24, v24, v25, vcc
	v_rsq_f32_e32 v24, v24
	s_nop 0
	v_mul_f32_e32 v25, 0x45800000, v24
	v_cndmask_b32_e32 v24, v24, v25, vcc
	v_mul_f32_e32 v42, 0.5, v24
	v_pk_mul_f32 v[26:27], v[70:71], v[42:43] op_sel_hi:[1,0]
	v_pk_mul_f32 v[46:47], v[80:81], v[42:43] op_sel_hi:[1,0]
	v_pk_mul_f32 v[34:35], v[34:35], v[42:43] op_sel_hi:[1,0]
	v_pk_mul_f32 v[36:37], v[36:37], v[42:43] op_sel_hi:[1,0]
	s_waitcnt vmcnt(0) lgkmcnt(0)
	v_pk_fma_f32 v[30:31], v[6:7], v[26:27], v[212:213]
	v_pk_mul_f32 v[22:23], v[72:73], v[42:43] op_sel_hi:[1,0]
	v_pk_mul_f32 v[26:27], v[76:77], v[42:43] op_sel_hi:[1,0]
	v_pk_fma_f32 v[32:33], v[8:9], v[22:23], v[214:215]
	v_pk_fma_f32 v[26:27], v[10:11], v[26:27], v[216:217]
	v_pk_mul_f32 v[22:23], v[78:79], v[42:43] op_sel_hi:[1,0]
	s_nop 0
	v_pk_fma_f32 v[28:29], v[12:13], v[22:23], v[218:219]
	v_pk_fma_f32 v[22:23], v[14:15], v[46:47], v[220:221]
	v_pk_mul_f32 v[46:47], v[82:83], v[42:43] op_sel_hi:[1,0]
	v_mov_b32_e32 v42, v31
	v_pk_fma_f32 v[24:25], v[16:17], v[46:47], v[222:223]
	v_mov_b32_e32 v43, v27
	v_pk_mul_f32 v[42:43], v[42:43], v[42:43]
	v_pk_fma_f32 v[34:35], v[18:19], v[34:35], v[224:225]
	v_pk_fma_f32 v[36:37], v[20:21], v[36:37], v[226:227]
	flat_store_dwordx4 v[40:41], v[30:33] nt
	flat_store_dwordx4 v[40:41], v[26:29] offset:1024 nt
	flat_store_dwordx4 v[40:41], v[22:25] offset:2048 nt
	flat_store_dwordx4 v[40:41], v[34:37] offset:3072 nt
	v_mov_b32_e32 v40, v30
	v_mov_b32_e32 v41, v26
	v_pk_fma_f32 v[40:41], v[40:41], v[40:41], v[42:43]
	v_mov_b32_e32 v42, v32
	v_mov_b32_e32 v43, v28
	v_pk_fma_f32 v[40:41], v[42:43], v[42:43], v[40:41]
	v_mov_b32_e32 v42, v33
	v_mov_b32_e32 v43, v29
	v_mov_b32_e32 v44, v35
	v_mov_b32_e32 v45, v23
	v_pk_fma_f32 v[40:41], v[42:43], v[42:43], v[40:41]
	v_mov_b32_e32 v42, v34
	v_mov_b32_e32 v43, v22
	v_pk_mul_f32 v[44:45], v[44:45], v[44:45]
	v_add_f32_e32 v0, v40, v41
	v_pk_fma_f32 v[42:43], v[42:43], v[42:43], v[44:45]
	v_mov_b32_e32 v44, v36
	v_mov_b32_e32 v45, v24
	v_pk_fma_f32 v[42:43], v[44:45], v[44:45], v[42:43]
	v_mov_b32_e32 v44, v37
	v_mov_b32_e32 v45, v25
	v_pk_fma_f32 v[42:43], v[44:45], v[44:45], v[42:43]
	s_nop 0
	v_add_f32_e32 v0, v43, v0
	v_add_f32_e32 v0, v42, v0
	ds_bpermute_b32 v40, v61, v0
	s_waitcnt lgkmcnt(0)
	v_add_f32_e32 v0, v0, v40
	ds_bpermute_b32 v40, v84, v0
	s_waitcnt lgkmcnt(0)
	v_add_f32_e32 v0, v0, v40
	ds_bpermute_b32 v40, v85, v0
	s_waitcnt lgkmcnt(0)
	v_add_f32_e32 v0, v0, v40
	ds_bpermute_b32 v40, v86, v0
	s_waitcnt lgkmcnt(0)
	v_add_f32_e32 v0, v0, v40
	ds_bpermute_b32 v40, v87, v0
	s_waitcnt lgkmcnt(0)
	v_add_f32_e32 v0, v0, v40
	ds_bpermute_b32 v40, v88, v0
	s_waitcnt lgkmcnt(0)
	v_add_f32_e32 v0, v0, v40
	v_fmamk_f32 v0, v0, 0x3a800000, v190
	v_cmp_gt_f32_e32 vcc, s0, v0
	v_mul_f32_e32 v40, 0x4b800000, v0
	v_readlane_b32 s0, v254, 21
	v_cndmask_b32_e32 v0, v0, v40, vcc
	v_rsq_f32_e32 v0, v0
	v_add_u32_e32 v58, s0, v58
	s_movk_i32 s0, 0x40ff
	v_mul_f32_e32 v40, 0x45800000, v0
	v_cndmask_b32_e32 v0, v0, v40, vcc
	v_mul_f32_e32 v30, v30, v0
	v_mul_f32_e32 v31, v31, v0
	v_mul_f32_e32 v30, v2, v30
	v_mul_f32_e32 v31, v3, v31
	v_mul_f32_e32 v32, v32, v0
	v_mul_f32_e32 v33, v33, v0
	v_mul_f32_e32 v32, v4, v32
	v_mul_f32_e32 v33, v5, v33
	v_cvt_pk_bf16_f32 v30, v30, v31
	v_cvt_pk_bf16_f32 v31, v32, v33
	flat_store_dwordx2 v[38:39], v[30:31]
	v_mul_f32_e32 v26, v26, v0
	v_mul_f32_e32 v27, v27, v0
	v_mul_f32_e32 v28, v28, v0
	v_mul_f32_e32 v29, v29, v0
	v_mul_f32_e32 v22, v22, v0
	v_mul_f32_e32 v23, v23, v0
	v_mul_f32_e32 v24, v24, v0
	v_mul_f32_e32 v25, v25, v0
	v_cmp_lt_i32_e32 vcc, s0, v58
	s_or_b64 s[16:17], vcc, s[16:17]
	v_mul_f32_e32 v26, v228, v26
	v_mul_f32_e32 v27, v229, v27
	v_mul_f32_e32 v28, v230, v28
	v_mul_f32_e32 v29, v231, v29
	v_cvt_pk_bf16_f32 v26, v26, v27
	v_cvt_pk_bf16_f32 v27, v28, v29
	flat_store_dwordx2 v[38:39], v[26:27] offset:512
	v_mul_f32_e32 v22, v232, v22
	v_mul_f32_e32 v23, v233, v23
	v_mul_f32_e32 v24, v234, v24
	v_mul_f32_e32 v25, v25, v235
	v_cvt_pk_bf16_f32 v22, v22, v23
	v_cvt_pk_bf16_f32 v23, v24, v25
	flat_store_dwordx2 v[38:39], v[22:23] offset:1024
	v_mul_f32_e32 v26, v34, v0
	v_mul_f32_e32 v22, v26, v236
	v_mul_f32_e32 v26, v35, v0
	v_mul_f32_e32 v23, v26, v237
	v_mul_f32_e32 v26, v36, v0
	v_mul_f32_e32 v0, v37, v0
	v_mul_f32_e32 v24, v26, v238
	v_mul_f32_e32 v0, v0, v239
	v_cvt_pk_bf16_f32 v22, v22, v23
	v_cvt_pk_bf16_f32 v23, v24, v0
	flat_store_dwordx2 v[38:39], v[22:23] offset:1536
	s_andn2_b64 exec, exec, s[16:17]
	s_cbranch_execz .LBB0_312
;   __device__ __forceinline__ unsigned char* ws() const { return reinterpret_cast<unsigned char*>(ld64(27 * 8)); }
; template <int MODE>
; __device__ __forceinline__ void phase_rows(const PRef& p, const float* __restrict__ vsrc, const float* __restrict__ g1, const float* __restrict__ g2, float coef, int nsplit) {
;     ...
;       const float4* bs = (MODE == 1) ? reinterpret_cast<const float4*>(row < MP ? xp + (size_t)row * DM : xs_ + (size_t)(row - MP) * DM) : reinterpret_cast<const float4*>(hbuf + (size_t)row * DM);
;       float4 v[4]; float ss = 0.f;
;       if (row < MP) {
; #pragma unroll
;         for (int i = 0; i < 4; ++i) { const u32x2 q = vs[lane + 64 * i];
;           v[i] = make_float4(__uint_as_float(q[0] << 16), __uint_as_float(q[0] & 0xffff0000u), __uint_as_float(q[1] << 16), __uint_as_float(q[1] & 0xffff0000u)); }
;       } else {
;         const float4* ps = reinterpret_cast<const float4*>((const float*)(p.ws() + WS_PART) + (size_t)(row - MP) * DM);
; #pragma unroll
;         for (int i = 0; i < 4; ++i) v[i] = ps[lane + 64 * i];
;         for (int k = 1; k < nsplit; ++k) {
; #pragma unroll
;           for (int i = 0; i < 4; ++i) { float4 t = ps[(size_t)k * (MS * DM / 4) + lane + 64 * i]; v[i].x += t.x; v[i].y += t.y; v[i].z += t.z; v[i].w += t.w; }
.LBB0_308:
	s_movk_i32 s0, 0x4000
	v_cmp_gt_i32_e32 vcc, s0, v58
	s_movk_i32 s0, 0x3fff
	v_add_u32_e32 v0, 0xffffc000, v58
	v_cmp_lt_i32_e64 s[6:7], s0, v58
	v_lshlrev_b64 v[74:75], 12, v[0:1]
	v_lshlrev_b32_e32 v0, 4, v60
	v_ashrrev_i32_e32 v241, 31, v58
	v_mov_b32_e32 v240, v58
	v_lshlrev_b64 v[240:241], 12, v[240:241]
	v_lshl_add_u64 v[240:241], s[10:11], 0, v[240:241]
	v_lshl_add_u64 v[242:243], s[12:13], 0, v[74:75]
	v_cndmask_b32_e32 v241, v243, v241, vcc
	v_cndmask_b32_e32 v240, v242, v240, vcc
	v_lshl_add_u64 v[240:241], v[240:241], 0, v[0:1]
	flat_load_dwordx4 v[212:215], v[240:241] nt
	flat_load_dwordx4 v[216:219], v[240:241] offset:1024 nt
	flat_load_dwordx4 v[220:223], v[240:241] offset:2048 nt
	flat_load_dwordx4 v[224:227], v[240:241] offset:3072 nt
	s_and_saveexec_b64 s[0:1], s[6:7]
	s_xor_b64 s[0:1], exec, s[0:1]
	s_cbranch_execz .LBB0_310
	v_readlane_b32 s4, v254, 5
	s_cmp_lg_u32 s4, -1
	s_cselect_b32 s6, s4, 0
	s_mov_b64 s[4:5], src_shared_base
	s_cselect_b32 s4, s5, 0
	v_mov_b32_e32 v23, s4
	v_readlane_b32 s4, v254, 6
	s_cmp_lg_u32 s4, -1
	v_mov_b32_e32 v22, s6
	s_cselect_b32 s4, s4, 0
	s_cselect_b32 s5, s5, 0
	flat_load_dword v24, v[22:23] sc0 sc1
	s_waitcnt vmcnt(0)
	v_mov_b32_e32 v22, s4
	v_mov_b32_e32 v23, s5
	flat_load_dword v22, v[22:23] sc0 sc1
	s_waitcnt vmcnt(0) lgkmcnt(0)
	v_readfirstlane_b32 s4, v24
	v_readfirstlane_b32 s5, v22
	s_nop 1
	v_lshl_add_u64 v[22:23], s[4:5], 0, v[74:75]
	v_lshl_add_u64 v[56:57], v[22:23], 0, v[0:1]
	s_mov_b64 s[4:5], 0xee00000
	v_add_co_u32_e64 v22, s[6:7], s49, v56
	v_lshl_add_u64 v[34:35], v[56:57], 0, s[4:5]
	s_nop 0
	v_addc_co_u32_e64 v23, s[6:7], 0, v57, s[6:7]
	s_mov_b32 s4, 0xef00000
	v_add_co_u32_e64 v38, s[6:7], s4, v56
	s_mov_b32 s4, 0xf000000
	s_nop 0
	v_addc_co_u32_e64 v39, s[6:7], 0, v57, s[6:7]
	v_add_co_u32_e64 v30, s[6:7], s4, v56
	s_mov_b32 s4, 0xf100000
	s_nop 0
	v_addc_co_u32_e64 v31, s[6:7], 0, v57, s[6:7]
	v_add_co_u32_e64 v26, s[6:7], s4, v56
	flat_load_dwordx4 v[40:43], v[22:23]
	flat_load_dwordx4 v[44:47], v[38:39]
	v_addc_co_u32_e64 v27, s[6:7], 0, v57, s[6:7]
	s_mov_b32 s4, 0xf200000
	flat_load_dwordx4 v[48:51], v[30:31]
	flat_load_dwordx4 v[52:55], v[26:27]
	v_add_co_u32_e64 v24, s[6:7], s4, v56
	s_mov_b32 s4, 0xf300000
	s_nop 0
	v_addc_co_u32_e64 v25, s[6:7], 0, v57, s[6:7]
	flat_load_dwordx4 v[70:73], v[24:25]
	s_waitcnt vmcnt(0) lgkmcnt(0)
	v_pk_add_f32 v[22:23], v[40:41], v[44:45]
	v_pk_add_f32 v[42:43], v[42:43], v[46:47]
	v_pk_add_f32 v[22:23], v[22:23], v[48:49]
	s_nop 0
	v_pk_add_f32 v[22:23], v[22:23], v[52:53]
	v_pk_add_f32 v[42:43], v[42:43], v[50:51]
	v_pk_add_f32 v[28:29], v[22:23], v[70:71]
	v_add_co_u32_e64 v22, s[6:7], s4, v56
	s_mov_b32 s4, 0xf400000
	s_nop 0
	v_addc_co_u32_e64 v23, s[6:7], 0, v57, s[6:7]
	flat_load_dwordx4 v[76:79], v[22:23]
	v_pk_add_f32 v[42:43], v[42:43], v[54:55]
	s_waitcnt vmcnt(0) lgkmcnt(0)
	v_pk_add_f32 v[32:33], v[28:29], v[76:77]
	v_add_co_u32_e64 v28, s[6:7], s4, v56
	s_mov_b32 s4, 0xf500000
	s_nop 0
	v_addc_co_u32_e64 v29, s[6:7], 0, v57, s[6:7]
	flat_load_dwordx4 v[80:83], v[28:29]
	v_pk_add_f32 v[42:43], v[42:43], v[72:73]
	s_waitcnt vmcnt(0) lgkmcnt(0)
	v_pk_add_f32 v[36:37], v[32:33], v[80:81]
	v_add_co_u32_e64 v32, s[6:7], s4, v56
	s_mov_b32 s4, 0xf600000
	s_nop 0
	v_addc_co_u32_e64 v33, s[6:7], 0, v57, s[6:7]
	flat_load_dwordx4 v[90:93], v[32:33]
	v_pk_add_f32 v[42:43], v[42:43], v[78:79]
	s_waitcnt vmcnt(0) lgkmcnt(0)
	v_pk_add_f32 v[40:41], v[36:37], v[90:91]
	v_add_co_u32_e64 v36, s[6:7], s4, v56
	s_mov_b32 s4, 0xf700000
	s_nop 0
	v_addc_co_u32_e64 v37, s[6:7], 0, v57, s[6:7]
	flat_load_dwordx4 v[94:97], v[36:37]
	v_pk_add_f32 v[42:43], v[42:43], v[82:83]
	s_waitcnt vmcnt(0) lgkmcnt(0)
	v_pk_add_f32 v[44:45], v[40:41], v[94:95]
	v_add_co_u32_e64 v40, s[6:7], s4, v56
	s_mov_b32 s4, 0xf800000
	s_nop 0
	v_addc_co_u32_e64 v41, s[6:7], 0, v57, s[6:7]
	flat_load_dwordx4 v[98:101], v[40:41]
	v_pk_add_f32 v[42:43], v[42:43], v[92:93]
	s_waitcnt vmcnt(0) lgkmcnt(0)
	v_pk_add_f32 v[48:49], v[44:45], v[98:99]
	v_add_co_u32_e64 v44, s[6:7], s4, v56
	v_pk_add_f32 v[42:43], v[42:43], v[96:97]
	s_nop 0
	v_addc_co_u32_e64 v45, s[6:7], 0, v57, s[6:7]
	flat_load_dwordx4 v[102:105], v[44:45]
	v_pk_add_f32 v[42:43], v[42:43], v[100:101]
	s_waitcnt vmcnt(0) lgkmcnt(0)
; template <int MODE>
; __device__ __forceinline__ void phase_rows(const PRef& p, const float* __restrict__ vsrc, const float* __restrict__ g1, const float* __restrict__ g2, float coef, int nsplit) {
;     ...
;         for (int k = 1; k < nsplit; ++k) {
; #pragma unroll
;           for (int i = 0; i < 4; ++i) { float4 t = ps[(size_t)k * (MS * DM / 4) + lane + 64 * i]; v[i].x += t.x; v[i].y += t.y; v[i].z += t.z; v[i].w += t.w; }
	v_pk_add_f32 v[70:71], v[48:49], v[102:103]
	flat_load_dwordx4 v[46:49], v[34:35] offset:1024
	flat_load_dwordx4 v[50:53], v[38:39] offset:1024
	flat_load_dwordx4 v[54:57], v[30:31] offset:1024
	flat_load_dwordx4 v[98:101], v[32:33] offset:1024
	flat_load_dwordx4 v[76:79], v[26:27] offset:1024
	flat_load_dwordx4 v[94:97], v[28:29] offset:1024
	flat_load_dwordx4 v[80:83], v[24:25] offset:1024
	flat_load_dwordx4 v[90:93], v[22:23] offset:1024
	v_pk_add_f32 v[72:73], v[42:43], v[104:105]
	flat_load_dwordx4 v[102:105], v[36:37] offset:1024
	flat_load_dwordx4 v[106:109], v[40:41] offset:1024
	flat_load_dwordx4 v[110:113], v[44:45] offset:1024
	s_waitcnt vmcnt(0) lgkmcnt(0)
	v_pk_add_f32 v[42:43], v[46:47], v[50:51]
	v_pk_add_f32 v[46:47], v[48:49], v[52:53]
	v_pk_add_f32 v[42:43], v[42:43], v[54:55]
	v_pk_add_f32 v[46:47], v[46:47], v[56:57]
	v_pk_add_f32 v[42:43], v[42:43], v[76:77]
	v_pk_add_f32 v[46:47], v[46:47], v[78:79]
	v_pk_add_f32 v[42:43], v[42:43], v[80:81]
	v_pk_add_f32 v[46:47], v[46:47], v[82:83]
	v_pk_add_f32 v[42:43], v[42:43], v[90:91]
	v_pk_add_f32 v[46:47], v[46:47], v[92:93]
	v_pk_add_f32 v[42:43], v[42:43], v[94:95]
	v_pk_add_f32 v[46:47], v[46:47], v[96:97]
	v_pk_add_f32 v[42:43], v[42:43], v[98:99]
	v_pk_add_f32 v[46:47], v[46:47], v[100:101]
	v_pk_add_f32 v[42:43], v[42:43], v[102:103]
	v_pk_add_f32 v[46:47], v[46:47], v[104:105]
	v_pk_add_f32 v[42:43], v[42:43], v[106:107]
	v_pk_add_f32 v[46:47], v[46:47], v[108:109]
	v_pk_add_f32 v[76:77], v[42:43], v[110:111]
	v_pk_add_f32 v[78:79], v[46:47], v[112:113]
	flat_load_dwordx4 v[46:49], v[34:35] offset:2048
	flat_load_dwordx4 v[50:53], v[38:39] offset:2048
	flat_load_dwordx4 v[54:57], v[30:31] offset:2048
	flat_load_dwordx4 v[102:105], v[32:33] offset:2048
	flat_load_dwordx4 v[80:83], v[26:27] offset:2048
	flat_load_dwordx4 v[98:101], v[28:29] offset:2048
	flat_load_dwordx4 v[90:93], v[24:25] offset:2048
	flat_load_dwordx4 v[94:97], v[22:23] offset:2048
	flat_load_dwordx4 v[106:109], v[36:37] offset:2048
	flat_load_dwordx4 v[110:113], v[40:41] offset:2048
	flat_load_dwordx4 v[114:117], v[44:45] offset:2048
	s_waitcnt vmcnt(0) lgkmcnt(0)
	v_pk_add_f32 v[42:43], v[46:47], v[50:51]
	v_pk_add_f32 v[46:47], v[48:49], v[52:53]
	v_pk_add_f32 v[42:43], v[42:43], v[54:55]
	v_pk_add_f32 v[46:47], v[46:47], v[56:57]
	v_pk_add_f32 v[42:43], v[42:43], v[80:81]
	v_pk_add_f32 v[46:47], v[46:47], v[82:83]
	v_pk_add_f32 v[42:43], v[42:43], v[90:91]
	v_pk_add_f32 v[46:47], v[46:47], v[92:93]
	v_pk_add_f32 v[42:43], v[42:43], v[94:95]
	v_pk_add_f32 v[46:47], v[46:47], v[96:97]
	v_pk_add_f32 v[42:43], v[42:43], v[98:99]
	v_pk_add_f32 v[46:47], v[46:47], v[100:101]
	v_pk_add_f32 v[42:43], v[42:43], v[102:103]
	v_pk_add_f32 v[46:47], v[46:47], v[104:105]
	v_pk_add_f32 v[42:43], v[42:43], v[106:107]
	v_pk_add_f32 v[46:47], v[46:47], v[108:109]
	v_pk_add_f32 v[42:43], v[42:43], v[110:111]
	v_pk_add_f32 v[46:47], v[46:47], v[112:113]
	v_pk_add_f32 v[80:81], v[42:43], v[114:115]
	v_pk_add_f32 v[82:83], v[46:47], v[116:117]
	flat_load_dwordx4 v[46:49], v[34:35] offset:3072
	flat_load_dwordx4 v[54:57], v[38:39] offset:3072
	s_waitcnt vmcnt(0) lgkmcnt(0)
	v_pk_add_f32 v[34:35], v[46:47], v[54:55]
	flat_load_dwordx4 v[52:55], v[30:31] offset:3072
	s_waitcnt vmcnt(0) lgkmcnt(0)
	v_pk_add_f32 v[30:31], v[34:35], v[52:53]
	flat_load_dwordx4 v[50:53], v[26:27] offset:3072
	s_nop 0
	flat_load_dwordx4 v[40:43], v[40:41] offset:3072
	s_waitcnt vmcnt(0) lgkmcnt(0)
	v_pk_add_f32 v[30:31], v[30:31], v[50:51]
	flat_load_dwordx4 v[24:27], v[24:25] offset:3072
	s_nop 0
	flat_load_dwordx4 v[36:39], v[36:37] offset:3072
	s_waitcnt vmcnt(0) lgkmcnt(0)
	v_pk_add_f32 v[30:31], v[30:31], v[24:25]
	flat_load_dwordx4 v[22:25], v[22:23] offset:3072
	s_nop 0
	flat_load_dwordx4 v[32:35], v[32:33] offset:3072
	s_waitcnt vmcnt(0) lgkmcnt(0)
	v_pk_add_f32 v[22:23], v[30:31], v[22:23]
	flat_load_dwordx4 v[28:31], v[28:29] offset:3072
	s_nop 0
	flat_load_dwordx4 v[44:47], v[44:45] offset:3072
	s_waitcnt vmcnt(0) lgkmcnt(0)
	v_pk_add_f32 v[22:23], v[22:23], v[28:29]
	v_pk_add_f32 v[28:29], v[48:49], v[56:57]
	v_pk_add_f32 v[22:23], v[22:23], v[32:33]
	v_pk_add_f32 v[28:29], v[28:29], v[54:55]
	v_pk_add_f32 v[22:23], v[22:23], v[36:37]
	v_pk_add_f32 v[28:29], v[28:29], v[52:53]
	v_pk_add_f32 v[22:23], v[22:23], v[40:41]
	v_pk_add_f32 v[26:27], v[28:29], v[26:27]
	s_nop 0
	v_pk_add_f32 v[24:25], v[26:27], v[24:25]
	s_nop 0
	v_pk_add_f32 v[24:25], v[24:25], v[30:31]
	s_nop 0
	v_pk_add_f32 v[24:25], v[24:25], v[34:35]
	v_pk_add_f32 v[34:35], v[22:23], v[44:45]
	v_pk_add_f32 v[24:25], v[24:25], v[38:39]
	s_nop 0
	v_pk_add_f32 v[24:25], v[24:25], v[42:43]
	s_nop 0
	v_pk_add_f32 v[36:37], v[24:25], v[46:47]

;   __device__ __forceinline__ const float* in(int i) const { return reinterpret_cast<const float*>(ld64(i * 8)); }
;   __device__ __forceinline__ float* out() const { return reinterpret_cast<float*>(ld64(26 * 8)); }
;   __device__ __forceinline__ unsigned char* ws() const { return reinterpret_cast<unsigned char*>(ld64(27 * 8)); }
; __device__ __forceinline__ int opaque_tid() { int t = threadIdx.x; asm volatile("" : "+v"(t)); return t; }
; template <int MODE>
; __device__ __forceinline__ void phase_rows(const PRef& p, const float* __restrict__ vsrc, const float* __restrict__ g1, const float* __restrict__ g2, float coef, int nsplit) {
;   const int tidx = opaque_tid();
;   const int lane = tidx & 63, wave = tidx >> 6;
;   bf16* xn = (bf16*)(p.ws() + WS_XN);
;   float* hbuf = p.out() + O_Y;
;   const float* xp = p.in(0); const float* xs_ = p.in(1);
;   for (int row = blockIdx.x * 8 + wave; row < MT; row += gridDim.x * 8) {
;     float4 h[4];
;     if (MODE == 0) {
;       const float4* xs = reinterpret_cast<const float4*>(row < MP ? xp + (size_t)row * DM : xs_ + (size_t)(row - MP) * DM);
; #pragma unroll
;       for (int i = 0; i < 4; ++i) { const f32x4v t = __builtin_nontemporal_load(reinterpret_cast<const f32x4v*>(xs) + lane + 64 * i); h[i] = make_float4(t[0], t[1], t[2], t[3]); }
;     ...
;       float4 g = reinterpret_cast<const float4*>(g2)[lane + 64 * i];
.LBB0_1166:
	s_add_i32 s0, 0, 0x23f30
	s_cmp_lg_u32 s0, -1
	s_cselect_b32 s0, s0, 0
	s_mov_b64 s[4:5], src_shared_base
	s_cselect_b32 s1, s5, 0
	v_mov_b32_e32 v2, s0
	s_add_i32 s0, 0, 0x23f34
	s_cmp_lg_u32 s0, -1
	v_mov_b32_e32 v3, s1
	s_cselect_b32 s0, s0, 0
	s_cselect_b32 s1, s5, 0
	flat_load_dword v0, v[2:3] sc0 sc1
	s_waitcnt vmcnt(0)
	v_mov_b32_e32 v2, s0
	v_mov_b32_e32 v3, s1
	flat_load_dword v2, v[2:3] sc0 sc1
	s_waitcnt vmcnt(0)
	v_readlane_b32 s0, v254, 5
	s_cmp_lg_u32 s0, -1
	s_cselect_b32 s0, s0, 0
	s_cselect_b32 s1, s5, 0
	v_mov_b32_e32 v3, s1
	s_waitcnt lgkmcnt(0)
	v_readfirstlane_b32 s8, v0
	v_mov_b32_e32 v0, v171
	v_readfirstlane_b32 s9, v2
	v_mov_b32_e32 v2, s0
	v_readlane_b32 s0, v254, 6
	s_cmp_lg_u32 s0, -1
	s_cselect_b32 s0, s0, 0
	s_cselect_b32 s1, s5, 0
	flat_load_dword v5, v[2:3] sc0 sc1
	s_waitcnt vmcnt(0)
	v_mov_b32_e32 v2, s0
	v_mov_b32_e32 v3, s1
	flat_load_dword v2, v[2:3] sc0 sc1
	s_waitcnt vmcnt(0)
	s_add_i32 s0, 0, 0x23fd0
	s_cmp_lg_u32 s0, -1
	s_cselect_b32 s0, s0, 0
	s_cselect_b32 s1, s5, 0
	v_mov_b32_e32 v3, s1
	v_ashrrev_i32_e32 v4, 6, v0
	s_waitcnt lgkmcnt(0)
	v_readfirstlane_b32 s10, v5
	v_readfirstlane_b32 s11, v2
	v_mov_b32_e32 v2, s0
	s_add_i32 s0, 0, 0x23fd4
	s_cmp_lg_u32 s0, -1
	flat_load_dword v2, v[2:3] sc0 sc1
	s_waitcnt vmcnt(0)
	s_cselect_b32 s0, s0, 0
	s_cselect_b32 s1, s5, 0
	s_waitcnt lgkmcnt(0)
	v_mov_b32_e32 v2, s0
	s_add_i32 s0, 0, 0x23f00
	v_mov_b32_e32 v3, s1
	s_cmp_lg_u32 s0, -1
	flat_load_dword v2, v[2:3] sc0 sc1
	s_waitcnt vmcnt(0)
	s_cselect_b32 s0, s0, 0
	s_cselect_b32 s1, s5, 0
	s_waitcnt lgkmcnt(0)
	v_mov_b32_e32 v2, s0
	s_add_i32 s0, 0, 0x23f04
	s_cmp_lg_u32 s0, -1
	v_mov_b32_e32 v3, s1
	s_cselect_b32 s0, s0, 0
	s_cselect_b32 s1, s5, 0
	flat_load_dword v5, v[2:3] sc0 sc1
	s_waitcnt vmcnt(0)
	v_mov_b32_e32 v2, s0
	v_mov_b32_e32 v3, s1
	flat_load_dword v2, v[2:3] sc0 sc1
	s_waitcnt vmcnt(0)
	s_add_i32 s4, 0, 0x23f08
	s_cmp_lg_u32 s4, -1
	s_cselect_b32 s4, s4, 0
	s_cselect_b32 s6, s5, 0
	v_mov_b32_e32 v3, s6
	v_readlane_b32 s6, v254, 42
	s_waitcnt lgkmcnt(0)
	v_readfirstlane_b32 s0, v5
	v_add_u32_e32 v10, s6, v4
	s_movk_i32 s6, 0x4100
	v_readfirstlane_b32 s1, v2
	v_mov_b32_e32 v2, s4
	s_add_i32 s4, 0, 0x23f0c
	s_cmp_lg_u32 s4, -1
	s_cselect_b32 s4, s4, 0
	s_cselect_b32 s5, s5, 0
	flat_load_dword v5, v[2:3] sc0 sc1
	s_waitcnt vmcnt(0)
	v_mov_b32_e32 v2, s4
	v_mov_b32_e32 v3, s5
	flat_load_dword v2, v[2:3] sc0 sc1
	s_waitcnt vmcnt(0)
	v_cmp_gt_i32_e32 vcc, s6, v10
	s_waitcnt lgkmcnt(0)
	v_readfirstlane_b32 s4, v5
	v_readfirstlane_b32 s5, v2
	s_and_saveexec_b64 s[6:7], vcc
	s_cbranch_execz .LBB0_1173
	v_and_b32_e32 v6, 63, v0
	v_lshlrev_b32_e32 v0, 4, v6
	v_lshl_add_u64 v[12:13], s[8:9], 0, v[0:1]
	flat_load_dwordx4 v[2:5], v[12:13]
	flat_load_dwordx4 v[228:231], v[12:13] offset:1024
	flat_load_dwordx4 v[232:235], v[12:13] offset:2048
	flat_load_dwordx4 v[236:239], v[12:13] offset:3072
	v_xor_b32_e32 v0, 32, v193
	v_cmp_lt_i32_e32 vcc, v0, v195
	s_mov_b64 s[8:9], 0x2a00000
	s_nop 0
	v_cndmask_b32_e32 v0, v193, v0, vcc
	v_cmp_lt_i32_e32 vcc, v253, v195
	v_lshlrev_b32_e32 v16, 2, v0
	s_nop 0
	v_cndmask_b32_e32 v0, v193, v253, vcc
	v_cmp_lt_i32_e32 vcc, v210, v195
	v_lshlrev_b32_e32 v17, 2, v0
	s_nop 0
	v_cndmask_b32_e32 v0, v193, v210, vcc
	v_lshlrev_b32_e32 v18, 2, v0
	v_xor_b32_e32 v0, 4, v193
	v_cmp_lt_i32_e32 vcc, v0, v195
	s_nop 1
	v_cndmask_b32_e32 v0, v193, v0, vcc
	v_lshlrev_b32_e32 v19, 2, v0
	v_xor_b32_e32 v0, 2, v193
	v_cmp_lt_i32_e32 vcc, v0, v195
	s_nop 1
	v_cndmask_b32_e32 v0, v193, v0, vcc
	v_lshlrev_b32_e32 v20, 2, v0
	v_xor_b32_e32 v0, 1, v193
	v_cmp_lt_i32_e32 vcc, v0, v195
	s_nop 1
	v_cndmask_b32_e32 v0, v193, v0, vcc
	v_lshlrev_b32_e32 v21, 2, v0
	v_lshlrev_b32_e32 v0, 3, v6
	v_lshl_add_u64 v[8:9], s[10:11], 0, v[0:1]
	v_lshl_add_u64 v[14:15], v[8:9], 0, s[8:9]
	s_mov_b64 s[8:9], 0
	v_lshlrev_b32_e32 v0, 4, v6
	s_branch .LBB0_1169
; template <int MODE>
; __device__ __forceinline__ void phase_rows(const PRef& p, const float* __restrict__ vsrc, const float* __restrict__ g1, const float* __restrict__ g2, float coef, int nsplit) {
;     ...
;     if (MODE == 0) {
;       const float4* xs = reinterpret_cast<const float4*>(row < MP ? xp + (size_t)row * DM : xs_ + (size_t)(row - MP) * DM);
; #pragma unroll
;       for (int i = 0; i < 4; ++i) { const f32x4v t = __builtin_nontemporal_load(reinterpret_cast<const f32x4v*>(xs) + lane + 64 * i); h[i] = make_float4(t[0], t[1], t[2], t[3]); }
;     } else {
;       const u32x2* vs = reinterpret_cast<const u32x2*>(reinterpret_cast<const bf16*>(vsrc) + (size_t)row * DM);
;       const float4* bs = (MODE == 1) ? reinterpret_cast<const float4*>(row < MP ? xp + (size_t)row * DM : xs_ + (size_t)(row - MP) * DM) : reinterpret_cast<const float4*>(hbuf + (size_t)row * DM);
;       float4 v[4]; float ss = 0.f;
;       if (row < MP) {
; #pragma unroll
;         for (int i = 0; i < 4; ++i) { const u32x2 q = vs[lane + 64 * i];
;           v[i] = make_float4(__uint_as_float(q[0] << 16), __uint_as_float(q[0] & 0xffff0000u), __uint_as_float(q[1] << 16), __uint_as_float(q[1] & 0xffff0000u)); }
;       } else {
;         const float4* ps = reinterpret_cast<const float4*>((const float*)(p.ws() + WS_PART) + (size_t)(row - MP) * DM);
; #pragma unroll
;         for (int i = 0; i < 4; ++i) v[i] = ps[lane + 64 * i];
;         for (int k = 1; k < nsplit; ++k) {
; #pragma unroll
;           for (int i = 0; i < 4; ++i) { float4 t = ps[(size_t)k * (MS * DM / 4) + lane + 64 * i]; v[i].x += t.x; v[i].y += t.y; v[i].z += t.z; v[i].w += t.w; }
;         }
;       }
; #pragma unroll
;       for (int i = 0; i < 4; ++i) ss += v[i].x * v[i].x + v[i].y * v[i].y + v[i].z * v[i].z + v[i].w * v[i].w;
;       ss = wave_sum(ss);
;       const float r = rsqrtf(ss * (1.f / DM) + RMS_EPS) * coef;
; #pragma unroll
;       for (int i = 0; i < 4; ++i) {
;         const f32x4v bt = __builtin_nontemporal_load(reinterpret_cast<const f32x4v*>(bs) + lane + 64 * i); const float4 b = make_float4(bt[0], bt[1], bt[2], bt[3]);
;         float4 g = reinterpret_cast<const float4*>(g1)[lane + 64 * i];
;         h[i].x = b.x + v[i].x * r * g.x; h[i].y = b.y + v[i].y * r * g.y; h[i].z = b.z + v[i].z * r * g.z; h[i].w = b.w + v[i].w * r * g.w;
;       }
;       if (MODE != 3) {
.LBB0_1168:
	s_or_b64 exec, exec, s[10:11]
	v_lshl_add_u64 v[6:7], v[6:7], 0, v[0:1]
	flat_load_dwordx4 v[22:25], v[6:7] nt
	flat_load_dwordx4 v[26:29], v[6:7] offset:1024 nt
	flat_load_dwordx4 v[30:33], v[6:7] offset:2048 nt
	s_nop 0
	flat_load_dwordx4 v[6:9], v[6:7] offset:3072 nt
	s_mov_b32 s10, 0x800000
	s_waitcnt vmcnt(0) lgkmcnt(0)
	v_mov_b32_e32 v36, v23
	v_mov_b32_e32 v37, v27
	v_mov_b32_e32 v34, v22
	v_mov_b32_e32 v35, v26
	v_pk_mul_f32 v[36:37], v[36:37], v[36:37]
	v_mov_b32_e32 v38, v31
	v_pk_fma_f32 v[34:35], v[34:35], v[34:35], v[36:37]
	v_mov_b32_e32 v36, v24
	v_mov_b32_e32 v37, v28
	v_pk_fma_f32 v[34:35], v[36:37], v[36:37], v[34:35]
	v_mov_b32_e32 v36, v25
	v_mov_b32_e32 v37, v29
	v_mov_b32_e32 v39, v7
	v_pk_fma_f32 v[34:35], v[36:37], v[36:37], v[34:35]
	v_mov_b32_e32 v36, v30
	v_mov_b32_e32 v37, v6
	v_pk_mul_f32 v[38:39], v[38:39], v[38:39]
	v_add_f32_e32 v34, v34, v35
	v_pk_fma_f32 v[36:37], v[36:37], v[36:37], v[38:39]
	v_mov_b32_e32 v38, v32
	v_mov_b32_e32 v39, v8
	v_pk_fma_f32 v[36:37], v[38:39], v[38:39], v[36:37]
	v_mov_b32_e32 v38, v33
	v_mov_b32_e32 v39, v9
	v_pk_fma_f32 v[36:37], v[38:39], v[38:39], v[36:37]
	s_nop 0
	v_add_f32_e32 v34, v34, v36
	v_add_f32_e32 v34, v34, v37
	ds_bpermute_b32 v35, v16, v34
	s_waitcnt lgkmcnt(0)
	v_add_f32_e32 v34, v34, v35
	ds_bpermute_b32 v35, v17, v34
	s_waitcnt lgkmcnt(0)
	v_add_f32_e32 v34, v34, v35
	ds_bpermute_b32 v35, v18, v34
	s_waitcnt lgkmcnt(0)
	v_add_f32_e32 v34, v34, v35
	ds_bpermute_b32 v35, v19, v34
	s_waitcnt lgkmcnt(0)
	v_add_f32_e32 v34, v34, v35
	ds_bpermute_b32 v35, v20, v34
	s_waitcnt lgkmcnt(0)
	v_add_f32_e32 v34, v34, v35
	ds_bpermute_b32 v35, v21, v34
	s_waitcnt lgkmcnt(0)
	v_add_f32_e32 v34, v34, v35
	v_fmamk_f32 v34, v34, 0x3a800000, v190
	v_cmp_gt_f32_e32 vcc, s10, v34
	v_mul_f32_e32 v35, 0x4b800000, v34
	v_readlane_b32 s10, v254, 21
	v_cndmask_b32_e32 v34, v34, v35, vcc
	v_rsq_f32_e32 v34, v34
	s_nop 0
	v_mul_f32_e32 v35, 0x45800000, v34
	v_cndmask_b32_e32 v36, v34, v35, vcc
	v_lshlrev_b64 v[34:35], 11, v[10:11]
	v_mul_f32_e32 v11, v22, v36
	v_mul_f32_e32 v22, v23, v36
	v_mul_f32_e32 v23, v24, v36
	v_mul_f32_e32 v22, v3, v22
	v_mul_f32_e32 v23, v4, v23
	v_mul_f32_e32 v24, v25, v36
	v_mul_f32_e32 v11, v2, v11
	v_mul_f32_e32 v24, v5, v24
	v_cvt_pk_bf16_f32 v22, v11, v22
	v_cvt_pk_bf16_f32 v23, v23, v24
	v_lshl_add_u64 v[34:35], v[14:15], 0, v[34:35]
	flat_store_dwordx2 v[34:35], v[22:23]
	v_mul_f32_e32 v11, v26, v36
	v_add_u32_e32 v10, s10, v10
	s_movk_i32 s10, 0x40ff
	v_mul_f32_e32 v6, v6, v36
	v_mul_f32_e32 v7, v7, v36
	v_cmp_lt_i32_e32 vcc, s10, v10
	v_mul_f32_e32 v8, v8, v36
	v_mul_f32_e32 v9, v9, v36
	s_or_b64 s[8:9], vcc, s[8:9]
	v_mul_f32_e32 v11, v228, v11
	v_mul_f32_e32 v22, v27, v36
	v_mul_f32_e32 v22, v229, v22
	v_mul_f32_e32 v23, v28, v36
	v_mul_f32_e32 v23, v230, v23
	v_mul_f32_e32 v24, v29, v36
	v_mul_f32_e32 v24, v231, v24
	v_cvt_pk_bf16_f32 v22, v11, v22
	v_cvt_pk_bf16_f32 v23, v23, v24
	flat_store_dwordx2 v[34:35], v[22:23] offset:512
	v_mul_f32_e32 v11, v30, v36
	v_mul_f32_e32 v11, v232, v11
	v_mul_f32_e32 v22, v31, v36
	v_mul_f32_e32 v22, v233, v22
	v_mul_f32_e32 v23, v32, v36
	v_mul_f32_e32 v23, v234, v23
	v_mul_f32_e32 v24, v33, v36
	v_mul_f32_e32 v24, v235, v24
	v_cvt_pk_bf16_f32 v22, v11, v22
	v_cvt_pk_bf16_f32 v23, v23, v24
	flat_store_dwordx2 v[34:35], v[22:23] offset:1024
	v_mul_f32_e32 v6, v6, v236
	v_mul_f32_e32 v7, v7, v237
	v_mul_f32_e32 v8, v8, v238
	v_mul_f32_e32 v9, v9, v239
	v_cvt_pk_bf16_f32 v6, v6, v7
	v_cvt_pk_bf16_f32 v7, v8, v9
	flat_store_dwordx2 v[34:35], v[6:7] offset:1536
	s_andn2_b64 exec, exec, s[8:9]
	s_cbranch_execz .LBB0_1173
